# in-proj GEMM: last K iteration peeled, 3/4 of the epilogue (scale, bf16 pack, stores) folded into its load phases
# baseline (speedup 1.0000x reference)
; #define PG8_STAGE(bufoff, gbase, voff) do { _Pragma("unroll") for (int _i = 0; _i < 2; ++_i) \
;         __builtin_amdgcn_global_load_lds((const unsigned*)((const char*)(gbase) + (voff)[_i]), (LAS unsigned*)(lds + (bufoff) + ldsw + _i * 8192), 16, 0, 0); } while (0)
; #define PG8_LDA(dst, b, h) do { _Pragma("unroll") for (int m = 0; m < 4; ++m) _Pragma("unroll") for (int k = 0; k < 2; ++k) dst[m][k] = *(const LAS bf16x8*)(lds + PG8_SA(b, h) + aoff + m * 2048 + k * 1024); } while (0)
; #define PG8_LDB(dst, b, h) do { _Pragma("unroll") for (int n = 0; n < 2; ++n) _Pragma("unroll") for (int k = 0; k < 2; ++k) dst[n][k] = *(const LAS bf16x8*)(lds + PG8_SB(b, h) + boff + n * 2048 + k * 1024); } while (0)
; #define PG8_MMA(ai, bj, At, Bt) do { __builtin_amdgcn_s_setprio(1); _Pragma("unroll") for (int m = 0; m < 4; ++m) _Pragma("unroll") for (int n = 0; n < 2; ++n) _Pragma("unroll") for (int k = 0; k < 2; ++k) \
;         acc[ai][bj][m][n] = __builtin_amdgcn_mfma_f32_16x16x32_bf16(Bt[n][k], At[m][k], acc[ai][bj][m][n], 0, 0, 0); __builtin_amdgcn_s_setprio(0); } while (0)
; #define PG8_BAR __builtin_amdgcn_s_barrier()
; template <class Epi>
; __device__ __forceinline__ void gemm_phase(LAS unsigned char* lds, const Gemm g, const StaticOrder& S, const Epi& E) {
;     ...
;         const char* nA = has_next ? (const char*)g.A + (size_t)nxt.pm * tstepA + (size_t)(nxt.pn >> 2) * gstepA : cA; const char* nB = has_next ? (const char*)g.Bt + (size_t)nxt.pn * tstepB : cB;
;         for (int t = 0; t < nt; t += 2) {
;             const bool last = (t == nt - 2);
;             const char* a1 = cA + (size_t)(t + 1) * kstepA;
;             const char* a2 = last ? nA : cA + (size_t)(t + 2) * kstepA; const char* b2 = last ? nB : cB + (size_t)(t + 2) * kstep;
;             const char* a3 = a2 + kstepA; const char* b3 = b2 + kstep;
;             PG8_LDB(B0, 0, 0); PG8_SCHED; PG8_LDA(At, 0, 0); PG8_STAGE(PG8_SA(1, 1), a1 + hstepA, voffA);
;             PG8_WAIT_L(8); PG8_BAR; PG8_WAIT_L(0); PG8_MMA(0, 0, At, B0); PG8_BAR; PG8_SCHED;
;     ...
; #pragma unroll
;         for (int a = 0; a < 2; ++a)
; #pragma unroll
;             for (int b = 0; b < 2; ++b)
; #pragma unroll
;                 for (int m = 0; m < 4; ++m)
; #pragma unroll
;                     for (int n = 0; n < 2; ++n) acc[a][b][m][n] = (f32x4){0.f, 0.f, 0.f, 0.f};
;         cur = nxt; cA = nA; cB = nB; ++ui;
.LBB0_157:
	s_ashr_i32 s23, s22, 31
	s_lshl_b64 s[24:25], s[22:23], 20
	s_add_u32 s26, s10, s24
	s_addc_u32 s27, s11, s25
	s_and_b64 s[24:25], s[40:41], exec
	s_cselect_b32 s23, s27, s39
	s_cselect_b32 s55, s26, s38
	s_ashr_i32 s21, s20, 31
	s_lshl_b64 s[24:25], s[20:21], 20
	s_add_u32 s36, s35, s24
	s_addc_u32 s37, s44, s25
	s_and_b64 s[24:25], s[40:41], exec
	s_cselect_b32 s21, s37, s5
	s_cselect_b32 s56, s36, s4
	s_add_u32 s57, s4, 0x100
	v_mov_b32_e32 v2, 0
	s_addc_u32 s58, s5, 0
	s_mov_b32 s59, -2
	v_mov_b32_e32 v3, v2
	v_mov_b32_e32 v4, v2
	v_mov_b32_e32 v5, v2
	v_mov_b32_e32 v6, v2
	v_mov_b32_e32 v7, v2
	v_mov_b32_e32 v8, v2
	v_mov_b32_e32 v9, v2
	v_mov_b32_e32 v18, v2
	v_mov_b32_e32 v19, v2
	v_mov_b32_e32 v20, v2
	v_mov_b32_e32 v21, v2
	v_mov_b32_e32 v22, v2
	v_mov_b32_e32 v23, v2
	v_mov_b32_e32 v24, v2
	v_mov_b32_e32 v25, v2
	v_mov_b32_e32 v34, v2
	v_mov_b32_e32 v35, v2
	v_mov_b32_e32 v36, v2
	v_mov_b32_e32 v37, v2
	v_mov_b32_e32 v38, v2
	v_mov_b32_e32 v39, v2
	v_mov_b32_e32 v40, v2
	v_mov_b32_e32 v41, v2
	v_mov_b32_e32 v50, v2
	v_mov_b32_e32 v51, v2
	v_mov_b32_e32 v52, v2
	v_mov_b32_e32 v53, v2
	v_mov_b32_e32 v54, v2
	v_mov_b32_e32 v55, v2
	v_mov_b32_e32 v56, v2
	v_mov_b32_e32 v57, v2
	v_mov_b32_e32 v10, v2
	v_mov_b32_e32 v11, v2
	v_mov_b32_e32 v12, v2
	v_mov_b32_e32 v13, v2
	v_mov_b32_e32 v14, v2
	v_mov_b32_e32 v15, v2
	v_mov_b32_e32 v16, v2
	v_mov_b32_e32 v17, v2
	v_mov_b32_e32 v26, v2
	v_mov_b32_e32 v27, v2
	v_mov_b32_e32 v28, v2
	v_mov_b32_e32 v29, v2
	v_mov_b32_e32 v30, v2
	v_mov_b32_e32 v31, v2
	v_mov_b32_e32 v32, v2
	v_mov_b32_e32 v33, v2
	v_mov_b32_e32 v42, v2
	v_mov_b32_e32 v43, v2
	v_mov_b32_e32 v44, v2
	v_mov_b32_e32 v45, v2
	v_mov_b32_e32 v46, v2
	v_mov_b32_e32 v47, v2
	v_mov_b32_e32 v48, v2
	v_mov_b32_e32 v49, v2
	v_mov_b32_e32 v58, v2
	v_mov_b32_e32 v59, v2
	v_mov_b32_e32 v60, v2
	v_mov_b32_e32 v61, v2
	v_mov_b32_e32 v62, v2
	v_mov_b32_e32 v63, v2
	v_mov_b32_e32 v64, v2
	v_mov_b32_e32 v65, v2
	v_mov_b32_e32 v66, v2
	v_mov_b32_e32 v67, v2
	v_mov_b32_e32 v68, v2
	v_mov_b32_e32 v69, v2
	v_mov_b32_e32 v70, v2
	v_mov_b32_e32 v71, v2
	v_mov_b32_e32 v72, v2
	v_mov_b32_e32 v73, v2
	v_mov_b32_e32 v82, v2
	v_mov_b32_e32 v83, v2
	v_mov_b32_e32 v84, v2
	v_mov_b32_e32 v85, v2
	v_mov_b32_e32 v86, v2
	v_mov_b32_e32 v87, v2
	v_mov_b32_e32 v88, v2
	v_mov_b32_e32 v89, v2
	v_mov_b32_e32 v98, v2
	v_mov_b32_e32 v99, v2
	v_mov_b32_e32 v100, v2
	v_mov_b32_e32 v101, v2
	v_mov_b32_e32 v102, v2
	v_mov_b32_e32 v103, v2
	v_mov_b32_e32 v104, v2
	v_mov_b32_e32 v105, v2
	v_mov_b32_e32 v114, v2
	v_mov_b32_e32 v115, v2
	v_mov_b32_e32 v116, v2
	v_mov_b32_e32 v117, v2
	v_mov_b32_e32 v118, v2
	v_mov_b32_e32 v119, v2
	v_mov_b32_e32 v120, v2
	v_mov_b32_e32 v121, v2
	v_mov_b32_e32 v74, v2
	v_mov_b32_e32 v75, v2
	v_mov_b32_e32 v76, v2
	v_mov_b32_e32 v77, v2
	v_mov_b32_e32 v78, v2
	v_mov_b32_e32 v79, v2
	v_mov_b32_e32 v80, v2
	v_mov_b32_e32 v81, v2
	v_mov_b32_e32 v90, v2
	v_mov_b32_e32 v91, v2
	v_mov_b32_e32 v92, v2
	v_mov_b32_e32 v93, v2
	v_mov_b32_e32 v94, v2
	v_mov_b32_e32 v95, v2
	v_mov_b32_e32 v96, v2
	v_mov_b32_e32 v97, v2
	v_mov_b32_e32 v106, v2
	v_mov_b32_e32 v107, v2
	v_mov_b32_e32 v108, v2
	v_mov_b32_e32 v109, v2
	v_mov_b32_e32 v110, v2
	v_mov_b32_e32 v111, v2
	v_mov_b32_e32 v112, v2
	v_mov_b32_e32 v113, v2
	v_mov_b32_e32 v122, v2
	v_mov_b32_e32 v123, v2
	v_mov_b32_e32 v124, v2
	v_mov_b32_e32 v125, v2
	v_mov_b32_e32 v126, v2
	v_mov_b32_e32 v127, v2
	v_mov_b32_e32 v128, v2
	v_mov_b32_e32 v129, v2
.LBB0_158:
	s_add_u32 s42, s38, 0x100
	s_addc_u32 s43, s39, 0
	s_add_i32 s60, 0, 0x10000
	v_add_u32_e32 v0, s60, v152
	ds_read_b128 v[146:149], v0
	ds_read_b128 v[162:165], v0 offset:1024
	ds_read_b128 v[166:169], v0 offset:2048
	ds_read_b128 v[170:173], v0 offset:3072
	s_cmp_eq_u32 s59, 28
	s_cselect_b32 s25, s23, s43
	s_cselect_b32 s24, s55, s42
	s_cselect_b32 s5, s21, s58
	s_cselect_b32 s4, s56, s57
	v_lshl_add_u64 v[150:151], s[38:39], 0, v[140:141]
	s_add_i32 m0, s46, 0xc000
	ds_read_b128 v[174:177], v154
	ds_read_b128 v[188:191], v154 offset:1024
	ds_read_b128 v[192:195], v154 offset:2048
	ds_read_b128 v[196:199], v154 offset:3072
	ds_read_b128 v[200:203], v154 offset:4096
	ds_read_b128 v[204:207], v154 offset:5120
	ds_read_b128 v[208:211], v154 offset:6144
	ds_read_b128 v[212:215], v154 offset:7168
	global_load_lds_dwordx4 v[150:151], off
	v_lshl_add_u64 v[150:151], s[38:39], 0, v[142:143]
	s_add_i32 m0, s46, 0xe000
	s_nop 0
	global_load_lds_dwordx4 v[150:151], off
	s_waitcnt lgkmcnt(8)
	s_barrier
	s_waitcnt lgkmcnt(0)
	s_setprio 1
	s_waitcnt lgkmcnt(0)
	v_mfma_f32_16x16x32_bf16 v[126:129], v[146:149], v[174:177], v[126:129]
	v_mfma_f32_16x16x32_bf16 v[122:125], v[166:169], v[174:177], v[122:125]
	v_mfma_f32_16x16x32_bf16 v[110:113], v[146:149], v[192:195], v[110:113]
	v_mfma_f32_16x16x32_bf16 v[106:109], v[166:169], v[192:195], v[106:109]
	v_mfma_f32_16x16x32_bf16 v[94:97], v[146:149], v[200:203], v[94:97]
	v_mfma_f32_16x16x32_bf16 v[90:93], v[166:169], v[200:203], v[90:93]
	v_mfma_f32_16x16x32_bf16 v[78:81], v[146:149], v[208:211], v[78:81]
	v_mfma_f32_16x16x32_bf16 v[74:77], v[166:169], v[208:211], v[74:77]
	v_mfma_f32_16x16x32_bf16 v[126:129], v[162:165], v[188:191], v[126:129]
	v_mfma_f32_16x16x32_bf16 v[122:125], v[170:173], v[188:191], v[122:125]
	v_mfma_f32_16x16x32_bf16 v[110:113], v[162:165], v[196:199], v[110:113]
	v_mfma_f32_16x16x32_bf16 v[106:109], v[170:173], v[196:199], v[106:109]
	v_mfma_f32_16x16x32_bf16 v[94:97], v[162:165], v[204:207], v[94:97]
	v_mfma_f32_16x16x32_bf16 v[90:93], v[170:173], v[204:207], v[90:93]
	v_mfma_f32_16x16x32_bf16 v[78:81], v[162:165], v[212:215], v[78:81]
	v_mfma_f32_16x16x32_bf16 v[74:77], v[170:173], v[212:215], v[74:77]
	s_setprio 0
	s_barrier
; #define PG8_STAGE(bufoff, gbase, voff) do { _Pragma("unroll") for (int _i = 0; _i < 2; ++_i) \
;         __builtin_amdgcn_global_load_lds((const unsigned*)((const char*)(gbase) + (voff)[_i]), (LAS unsigned*)(lds + (bufoff) + ldsw + _i * 8192), 16, 0, 0); } while (0)
; #define PG8_LDA(dst, b, h) do { _Pragma("unroll") for (int m = 0; m < 4; ++m) _Pragma("unroll") for (int k = 0; k < 2; ++k) dst[m][k] = *(const LAS bf16x8*)(lds + PG8_SA(b, h) + aoff + m * 2048 + k * 1024); } while (0)
; #define PG8_LDB(dst, b, h) do { _Pragma("unroll") for (int n = 0; n < 2; ++n) _Pragma("unroll") for (int k = 0; k < 2; ++k) dst[n][k] = *(const LAS bf16x8*)(lds + PG8_SB(b, h) + boff + n * 2048 + k * 1024); } while (0)
; #define PG8_MMA(ai, bj, At, Bt) do { __builtin_amdgcn_s_setprio(1); _Pragma("unroll") for (int m = 0; m < 4; ++m) _Pragma("unroll") for (int n = 0; n < 2; ++n) _Pragma("unroll") for (int k = 0; k < 2; ++k) \
;         acc[ai][bj][m][n] = __builtin_amdgcn_mfma_f32_16x16x32_bf16(Bt[n][k], At[m][k], acc[ai][bj][m][n], 0, 0, 0); __builtin_amdgcn_s_setprio(0); } while (0)
; #define PG8_WAIT_V(n) asm volatile("s_waitcnt vmcnt(" #n ")" ::: "memory")
; #define PG8_WAIT_L(n) asm volatile("s_waitcnt lgkmcnt(" #n ")" ::: "memory")
; #define PG8_BAR __builtin_amdgcn_s_barrier()
; #define PG8_SCHED __builtin_amdgcn_sched_barrier(0)
; template <class Epi>
; __device__ __forceinline__ void gemm_phase(LAS unsigned char* lds, const Gemm g, const StaticOrder& S, const Epi& E) {
;     ...
;             PG8_LDB(B1, 0, 1); PG8_STAGE(PG8_SB(0, 0), b2, voffB);
;             PG8_BAR; PG8_WAIT_L(0); PG8_MMA(0, 1, At, B1); PG8_BAR;
;             PG8_LDA(At, 0, 1); PG8_STAGE(PG8_SA(0, 0), a2, voffA);
;             PG8_BAR; PG8_WAIT_L(0); PG8_MMA(1, 0, At, B0); PG8_BAR; PG8_SCHED;
;             PG8_STAGE(PG8_SB(0, 1), b2 + hstepB, voffB);
;             PG8_WAIT_V(6); PG8_BAR; PG8_MMA(1, 1, At, B1); PG8_BAR;
;             PG8_LDB(B0, 1, 0); PG8_SCHED; PG8_LDA(At, 1, 0); PG8_STAGE(PG8_SA(0, 1), a2 + hstepA, voffA);
;             PG8_WAIT_L(8); PG8_BAR; PG8_WAIT_L(0); PG8_MMA(0, 0, At, B0); PG8_BAR; PG8_SCHED;
	s_add_i32 s61, 0, 0x14000
	s_add_i32 s38, s60, s45
	v_add_u32_e32 v0, s61, v152
	v_lshl_add_u64 v[150:151], s[4:5], 0, v[134:135]
	s_mov_b32 m0, s38
	ds_read_b128 v[216:219], v0
	ds_read_b128 v[220:223], v0 offset:1024
	ds_read_b128 v[224:227], v0 offset:2048
	ds_read_b128 v[228:231], v0 offset:3072
	global_load_lds_dwordx4 v[150:151], off
	v_lshl_add_u64 v[184:185], s[4:5], 0, v[130:131]
	s_add_i32 m0, s38, 0x2000
	s_nop 0
	global_load_lds_dwordx4 v[184:185], off
	s_barrier
	s_waitcnt lgkmcnt(0)
	s_setprio 1
	s_waitcnt lgkmcnt(0)
	v_mfma_f32_16x16x32_bf16 v[118:121], v[216:219], v[174:177], v[118:121]
	v_mfma_f32_16x16x32_bf16 v[114:117], v[224:227], v[174:177], v[114:117]
	v_mfma_f32_16x16x32_bf16 v[102:105], v[216:219], v[192:195], v[102:105]
	v_mfma_f32_16x16x32_bf16 v[98:101], v[224:227], v[192:195], v[98:101]
	v_mfma_f32_16x16x32_bf16 v[86:89], v[216:219], v[200:203], v[86:89]
	v_mfma_f32_16x16x32_bf16 v[82:85], v[224:227], v[200:203], v[82:85]
	v_mfma_f32_16x16x32_bf16 v[70:73], v[216:219], v[208:211], v[70:73]
	v_mfma_f32_16x16x32_bf16 v[66:69], v[224:227], v[208:211], v[66:69]
	v_mfma_f32_16x16x32_bf16 v[118:121], v[220:223], v[188:191], v[118:121]
	v_mfma_f32_16x16x32_bf16 v[114:117], v[228:231], v[188:191], v[114:117]
	v_mfma_f32_16x16x32_bf16 v[102:105], v[220:223], v[196:199], v[102:105]
	v_mfma_f32_16x16x32_bf16 v[98:101], v[228:231], v[196:199], v[98:101]
	v_mfma_f32_16x16x32_bf16 v[86:89], v[220:223], v[204:207], v[86:89]
	v_mfma_f32_16x16x32_bf16 v[82:85], v[228:231], v[204:207], v[82:85]
	v_mfma_f32_16x16x32_bf16 v[70:73], v[220:223], v[212:215], v[70:73]
	v_mfma_f32_16x16x32_bf16 v[66:69], v[228:231], v[212:215], v[66:69]
	s_setprio 0
	s_mov_b32 m0, s46
	v_lshl_add_u64 v[186:187], s[24:25], 0, v[136:137]
	s_barrier
	ds_read_b128 v[174:177], v154 offset:16384
	ds_read_b128 v[188:191], v154 offset:17408
	ds_read_b128 v[192:195], v154 offset:18432
	ds_read_b128 v[196:199], v154 offset:19456
	ds_read_b128 v[200:203], v154 offset:20480
	ds_read_b128 v[204:207], v154 offset:21504
	ds_read_b128 v[208:211], v154 offset:22528
	ds_read_b128 v[212:215], v154 offset:23552
	global_load_lds_dwordx4 v[186:187], off
	v_lshl_add_u64 v[244:245], s[24:25], 0, v[132:133]
	s_mov_b32 m0, s47
	s_nop 0
	global_load_lds_dwordx4 v[244:245], off
	s_barrier
	s_waitcnt lgkmcnt(0)
	s_setprio 1
	s_waitcnt lgkmcnt(0)
	v_mfma_f32_16x16x32_bf16 v[62:65], v[146:149], v[174:177], v[62:65]
	v_mfma_f32_16x16x32_bf16 v[58:61], v[166:169], v[174:177], v[58:61]
	v_mfma_f32_16x16x32_bf16 v[46:49], v[146:149], v[192:195], v[46:49]
	v_mfma_f32_16x16x32_bf16 v[42:45], v[166:169], v[192:195], v[42:45]
	v_mfma_f32_16x16x32_bf16 v[30:33], v[146:149], v[200:203], v[30:33]
	v_mfma_f32_16x16x32_bf16 v[26:29], v[166:169], v[200:203], v[26:29]
	v_mfma_f32_16x16x32_bf16 v[14:17], v[146:149], v[208:211], v[14:17]
	v_mfma_f32_16x16x32_bf16 v[10:13], v[166:169], v[208:211], v[10:13]
	v_mfma_f32_16x16x32_bf16 v[62:65], v[162:165], v[188:191], v[62:65]
	v_mfma_f32_16x16x32_bf16 v[58:61], v[170:173], v[188:191], v[58:61]
	v_mfma_f32_16x16x32_bf16 v[46:49], v[162:165], v[196:199], v[46:49]
	v_mfma_f32_16x16x32_bf16 v[42:45], v[170:173], v[196:199], v[42:45]
	v_mfma_f32_16x16x32_bf16 v[30:33], v[162:165], v[204:207], v[30:33]
	v_mfma_f32_16x16x32_bf16 v[26:29], v[170:173], v[204:207], v[26:29]
	v_mfma_f32_16x16x32_bf16 v[14:17], v[162:165], v[212:215], v[14:17]
	v_mfma_f32_16x16x32_bf16 v[10:13], v[170:173], v[212:215], v[10:13]
	s_setprio 0
	s_barrier
	s_add_u32 s38, s4, 0x80000
	s_addc_u32 s39, s5, 0
	s_add_i32 s60, s61, s45
	v_lshl_add_u64 v[146:147], s[38:39], 0, v[134:135]
	s_mov_b32 m0, s60
	s_nop 0
	global_load_lds_dwordx4 v[146:147], off
	v_lshl_add_u64 v[146:147], s[38:39], 0, v[130:131]
	s_add_i32 m0, s60, 0x2000
	s_nop 0
	global_load_lds_dwordx4 v[146:147], off
	s_waitcnt vmcnt(6)
	s_barrier
	s_setprio 1
	v_mfma_f32_16x16x32_bf16 v[54:57], v[216:219], v[174:177], v[54:57]
	v_mfma_f32_16x16x32_bf16 v[50:53], v[224:227], v[174:177], v[50:53]
	v_mfma_f32_16x16x32_bf16 v[38:41], v[216:219], v[192:195], v[38:41]
	v_mfma_f32_16x16x32_bf16 v[34:37], v[224:227], v[192:195], v[34:37]
	v_mfma_f32_16x16x32_bf16 v[22:25], v[216:219], v[200:203], v[22:25]
	v_mfma_f32_16x16x32_bf16 v[18:21], v[224:227], v[200:203], v[18:21]
	v_mfma_f32_16x16x32_bf16 v[6:9], v[216:219], v[208:211], v[6:9]
	v_mfma_f32_16x16x32_bf16 v[2:5], v[224:227], v[208:211], v[2:5]
	v_mfma_f32_16x16x32_bf16 v[54:57], v[220:223], v[188:191], v[54:57]
	v_mfma_f32_16x16x32_bf16 v[50:53], v[228:231], v[188:191], v[50:53]
	v_mfma_f32_16x16x32_bf16 v[38:41], v[220:223], v[196:199], v[38:41]
	v_mfma_f32_16x16x32_bf16 v[34:37], v[228:231], v[196:199], v[34:37]
	v_mfma_f32_16x16x32_bf16 v[22:25], v[220:223], v[204:207], v[22:25]
	v_mfma_f32_16x16x32_bf16 v[18:21], v[228:231], v[204:207], v[18:21]
	v_mfma_f32_16x16x32_bf16 v[6:9], v[220:223], v[212:215], v[6:9]
	v_mfma_f32_16x16x32_bf16 v[2:5], v[228:231], v[212:215], v[2:5]
	s_setprio 0
	s_add_i32 s38, 0, 0x18000
	v_add_u32_e32 v0, s38, v152
	s_barrier
	ds_read_b128 v[146:149], v0
	ds_read_b128 v[162:165], v0 offset:1024
	ds_read_b128 v[166:169], v0 offset:2048
	ds_read_b128 v[170:173], v0 offset:3072
	s_add_u32 s24, s24, 0x80000
	s_addc_u32 s25, s25, 0
	s_mov_b32 m0, s48
	v_lshl_add_u64 v[216:217], s[24:25], 0, v[136:137]
	ds_read_b128 v[174:177], v154 offset:32768
	ds_read_b128 v[188:191], v154 offset:33792
	ds_read_b128 v[192:195], v154 offset:34816
	ds_read_b128 v[196:199], v154 offset:35840
	ds_read_b128 v[200:203], v154 offset:36864
	ds_read_b128 v[204:207], v154 offset:37888
	ds_read_b128 v[208:211], v154 offset:38912
	ds_read_b128 v[212:215], v154 offset:39936
	global_load_lds_dwordx4 v[216:217], off
	v_lshl_add_u64 v[216:217], s[24:25], 0, v[132:133]
	s_mov_b32 m0, s49
	s_nop 0
	global_load_lds_dwordx4 v[216:217], off
	s_waitcnt lgkmcnt(8)
	s_barrier
; __device__ __forceinline__ unsigned cvt_pk_bf16(float lo, float hi) { unsigned r; asm volatile("v_cvt_pk_bf16_f32 %0, %1, %2" : "=v"(r) : "v"(lo), "v"(hi)); return r; }
; #define PG8_STAGE(bufoff, gbase, voff) do { _Pragma("unroll") for (int _i = 0; _i < 2; ++_i) \
;         __builtin_amdgcn_global_load_lds((const unsigned*)((const char*)(gbase) + (voff)[_i]), (LAS unsigned*)(lds + (bufoff) + ldsw + _i * 8192), 16, 0, 0); } while (0)
; #define PG8_LDA(dst, b, h) do { _Pragma("unroll") for (int m = 0; m < 4; ++m) _Pragma("unroll") for (int k = 0; k < 2; ++k) dst[m][k] = *(const LAS bf16x8*)(lds + PG8_SA(b, h) + aoff + m * 2048 + k * 1024); } while (0)
; #define PG8_WAIT_V(n) asm volatile("s_waitcnt vmcnt(" #n ")" ::: "memory")
; #define PG8_WAIT_L(n) asm volatile("s_waitcnt lgkmcnt(" #n ")" ::: "memory")
; template <class Epi>
; __device__ __forceinline__ void gemm_phase(LAS unsigned char* lds, const Gemm g, const StaticOrder& S, const Epi& E) {
;     ...
;             PG8_LDB(B1, 1, 1); PG8_STAGE(PG8_SB(1, 0), b3, voffB);
;             PG8_BAR; PG8_WAIT_L(0); PG8_MMA(0, 1, At, B1); PG8_BAR;
;             PG8_LDA(At, 1, 1); PG8_STAGE(PG8_SA(1, 0), a3, voffA);
;             PG8_BAR; PG8_WAIT_L(0); PG8_MMA(1, 0, At, B0); PG8_BAR; PG8_SCHED;
;             PG8_STAGE(PG8_SB(1, 1), b3 + hstepB, voffB);
;             PG8_WAIT_V(6); PG8_BAR; PG8_MMA(1, 1, At, B1); PG8_BAR;
;     __device__ __forceinline__ void operator()(const f32x4 (&acc)[2][2][4][2], const Unit& u, int wr, int wc, int fr, int fq, const Pre& pp) const {
;         const int row0 = u.pm * BM + wr * 64 + fr, col0 = u.pn * BM + wc * 32 + 8 * fq;
;         const bool gm = (UG != nullptr) && (u.pn < DE / BM);
;         const float (&rs)[8] = pp.rs;
; #pragma unroll
;         for (int ai = 0; ai < 2; ++ai)
; #pragma unroll
;             for (int m = 0; m < 4; ++m) { const int r = row0 + ai * HALF + m * 16; const float inv = rsqrtf(rs[ai * 4 + m] * (1.0f / DM) + EPS);
; #pragma unroll
;                 for (int bj = 0; bj < 2; ++bj) { const f32x4 v0 = acc[ai][bj][m][0] * inv, v1 = acc[ai][bj][m][1] * inv; const int c = col0 + bj * HALF;
;                     u32x4 w; w.x = cvt_pk_bf16(v0[0], v0[1]); w.y = cvt_pk_bf16(v0[2], v0[3]); w.z = cvt_pk_bf16(v1[0], v1[1]); w.w = cvt_pk_bf16(v1[2], v1[3]);
;                     bf16_t* dst = gm ? UG + (size_t)(c >> 4) * GSTR + r * 16 + (c & 15) : O + (size_t)r * DE2 + c;
	s_waitcnt lgkmcnt(0)
	s_setprio 1
	s_waitcnt lgkmcnt(0)
	v_mfma_f32_16x16x32_bf16 v[126:129], v[146:149], v[174:177], v[126:129]
	v_mfma_f32_16x16x32_bf16 v[122:125], v[166:169], v[174:177], v[122:125]
	v_mfma_f32_16x16x32_bf16 v[110:113], v[146:149], v[192:195], v[110:113]
	v_mfma_f32_16x16x32_bf16 v[106:109], v[166:169], v[192:195], v[106:109]
	v_mfma_f32_16x16x32_bf16 v[94:97], v[146:149], v[200:203], v[94:97]
	v_mfma_f32_16x16x32_bf16 v[90:93], v[166:169], v[200:203], v[90:93]
	v_mfma_f32_16x16x32_bf16 v[78:81], v[146:149], v[208:211], v[78:81]
	v_mfma_f32_16x16x32_bf16 v[74:77], v[166:169], v[208:211], v[74:77]
	v_mfma_f32_16x16x32_bf16 v[126:129], v[162:165], v[188:191], v[126:129]
	v_mfma_f32_16x16x32_bf16 v[122:125], v[170:173], v[188:191], v[122:125]
	v_mfma_f32_16x16x32_bf16 v[110:113], v[162:165], v[196:199], v[110:113]
	v_mfma_f32_16x16x32_bf16 v[106:109], v[170:173], v[196:199], v[106:109]
	v_mfma_f32_16x16x32_bf16 v[94:97], v[162:165], v[204:207], v[94:97]
	v_mfma_f32_16x16x32_bf16 v[90:93], v[170:173], v[204:207], v[90:93]
	v_mfma_f32_16x16x32_bf16 v[78:81], v[162:165], v[212:215], v[78:81]
	v_mfma_f32_16x16x32_bf16 v[74:77], v[170:173], v[212:215], v[74:77]
	s_setprio 0
	s_barrier
	s_add_i32 s24, 0, 0x1c000
	s_add_i32 s25, s38, s45
	v_add_u32_e32 v0, s24, v152
	v_lshl_add_u64 v[150:151], v[150:151], 0, s[6:7]
	s_mov_b32 m0, s25
	ds_read_b128 v[216:219], v0
	ds_read_b128 v[220:223], v0 offset:1024
	ds_read_b128 v[224:227], v0 offset:2048
	ds_read_b128 v[228:231], v0 offset:3072
	global_load_lds_dwordx4 v[150:151], off
	v_lshl_add_u64 v[150:151], v[184:185], 0, s[6:7]
	s_add_i32 m0, s25, 0x2000
	s_nop 0
	global_load_lds_dwordx4 v[150:151], off
	s_barrier
	s_waitcnt lgkmcnt(0)
	s_setprio 1
	s_waitcnt lgkmcnt(0)
	v_mfma_f32_16x16x32_bf16 v[118:121], v[216:219], v[174:177], v[118:121]
	v_mfma_f32_16x16x32_bf16 v[114:117], v[224:227], v[174:177], v[114:117]
	v_mfma_f32_16x16x32_bf16 v[102:105], v[216:219], v[192:195], v[102:105]
	v_mfma_f32_16x16x32_bf16 v[98:101], v[224:227], v[192:195], v[98:101]
	v_mfma_f32_16x16x32_bf16 v[86:89], v[216:219], v[200:203], v[86:89]
	v_mfma_f32_16x16x32_bf16 v[82:85], v[224:227], v[200:203], v[82:85]
	v_mfma_f32_16x16x32_bf16 v[70:73], v[216:219], v[208:211], v[70:73]
	v_mfma_f32_16x16x32_bf16 v[66:69], v[224:227], v[208:211], v[66:69]
	v_mfma_f32_16x16x32_bf16 v[118:121], v[220:223], v[188:191], v[118:121]
	v_mfma_f32_16x16x32_bf16 v[114:117], v[228:231], v[188:191], v[114:117]
	v_mfma_f32_16x16x32_bf16 v[102:105], v[220:223], v[196:199], v[102:105]
	v_mfma_f32_16x16x32_bf16 v[98:101], v[228:231], v[196:199], v[98:101]
	v_mfma_f32_16x16x32_bf16 v[86:89], v[220:223], v[204:207], v[86:89]
	v_mfma_f32_16x16x32_bf16 v[82:85], v[228:231], v[204:207], v[82:85]
	v_mfma_f32_16x16x32_bf16 v[70:73], v[220:223], v[212:215], v[70:73]
	v_mfma_f32_16x16x32_bf16 v[66:69], v[228:231], v[212:215], v[66:69]
	s_setprio 0
	s_mov_b32 m0, s50
	v_lshl_add_u64 v[150:151], v[186:187], 0, s[6:7]
	s_barrier
	ds_read_b128 v[174:177], v154 offset:49152
	ds_read_b128 v[188:191], v154 offset:50176
	ds_read_b128 v[192:195], v154 offset:51200
	ds_read_b128 v[196:199], v154 offset:52224
	ds_read_b128 v[200:203], v154 offset:53248
	ds_read_b128 v[204:207], v154 offset:54272
	ds_read_b128 v[208:211], v154 offset:55296
	ds_read_b128 v[212:215], v154 offset:56320
	global_load_lds_dwordx4 v[150:151], off
	v_lshl_add_u64 v[150:151], v[244:245], 0, s[6:7]
	s_mov_b32 m0, s51
	s_nop 0
	global_load_lds_dwordx4 v[150:151], off
	s_barrier
	s_waitcnt lgkmcnt(0)
	s_setprio 1
	s_waitcnt lgkmcnt(0)
	v_mfma_f32_16x16x32_bf16 v[62:65], v[146:149], v[174:177], v[62:65]
	v_mfma_f32_16x16x32_bf16 v[58:61], v[166:169], v[174:177], v[58:61]
	v_mfma_f32_16x16x32_bf16 v[46:49], v[146:149], v[192:195], v[46:49]
	v_mfma_f32_16x16x32_bf16 v[42:45], v[166:169], v[192:195], v[42:45]
	v_mfma_f32_16x16x32_bf16 v[30:33], v[146:149], v[200:203], v[30:33]
	v_mfma_f32_16x16x32_bf16 v[26:29], v[166:169], v[200:203], v[26:29]
	v_mfma_f32_16x16x32_bf16 v[14:17], v[146:149], v[208:211], v[14:17]
	v_mfma_f32_16x16x32_bf16 v[10:13], v[166:169], v[208:211], v[10:13]
	v_mfma_f32_16x16x32_bf16 v[62:65], v[162:165], v[188:191], v[62:65]
	v_mfma_f32_16x16x32_bf16 v[58:61], v[170:173], v[188:191], v[58:61]
	v_mfma_f32_16x16x32_bf16 v[46:49], v[162:165], v[196:199], v[46:49]
	v_mfma_f32_16x16x32_bf16 v[42:45], v[170:173], v[196:199], v[42:45]
	v_mfma_f32_16x16x32_bf16 v[30:33], v[162:165], v[204:207], v[30:33]
	v_mfma_f32_16x16x32_bf16 v[26:29], v[170:173], v[204:207], v[26:29]
	v_mfma_f32_16x16x32_bf16 v[14:17], v[162:165], v[212:215], v[14:17]
	v_mfma_f32_16x16x32_bf16 v[10:13], v[170:173], v[212:215], v[10:13]
	s_setprio 0
	s_barrier
	s_add_u32 s4, s4, 0x80080
	s_addc_u32 s5, s5, 0
	s_add_i32 s24, s24, s45
	v_lshl_add_u64 v[146:147], s[4:5], 0, v[134:135]
	s_mov_b32 m0, s24
	s_nop 0
	global_load_lds_dwordx4 v[146:147], off
	v_lshl_add_u64 v[146:147], s[4:5], 0, v[130:131]
	s_add_i32 m0, s24, 0x2000
	s_nop 0
	global_load_lds_dwordx4 v[146:147], off
	s_waitcnt vmcnt(6)
	s_barrier
	s_setprio 1
	v_mfma_f32_16x16x32_bf16 v[54:57], v[216:219], v[174:177], v[54:57]
	v_mfma_f32_16x16x32_bf16 v[50:53], v[224:227], v[174:177], v[50:53]
	v_mfma_f32_16x16x32_bf16 v[38:41], v[216:219], v[192:195], v[38:41]
	v_mfma_f32_16x16x32_bf16 v[34:37], v[224:227], v[192:195], v[34:37]
	v_mfma_f32_16x16x32_bf16 v[22:25], v[216:219], v[200:203], v[22:25]
	v_mfma_f32_16x16x32_bf16 v[18:21], v[224:227], v[200:203], v[18:21]
	v_mfma_f32_16x16x32_bf16 v[6:9], v[216:219], v[208:211], v[6:9]
	v_mfma_f32_16x16x32_bf16 v[2:5], v[224:227], v[208:211], v[2:5]
	v_mfma_f32_16x16x32_bf16 v[54:57], v[220:223], v[188:191], v[54:57]
	v_mfma_f32_16x16x32_bf16 v[50:53], v[228:231], v[188:191], v[50:53]
	v_mfma_f32_16x16x32_bf16 v[38:41], v[220:223], v[196:199], v[38:41]
	v_mfma_f32_16x16x32_bf16 v[34:37], v[228:231], v[196:199], v[34:37]
	v_mfma_f32_16x16x32_bf16 v[22:25], v[220:223], v[204:207], v[22:25]
	v_mfma_f32_16x16x32_bf16 v[18:21], v[228:231], v[204:207], v[18:21]
	v_mfma_f32_16x16x32_bf16 v[6:9], v[220:223], v[212:215], v[6:9]
	v_mfma_f32_16x16x32_bf16 v[2:5], v[228:231], v[212:215], v[2:5]
	s_setprio 0
	s_add_i32 s59, s59, 2
	s_add_u32 s57, s57, 0x100
	s_addc_u32 s58, s58, 0
	s_cmp_gt_u32 s59, 27
	s_mov_b64 s[38:39], s[42:43]
	s_barrier
	s_cbranch_scc0 .LBB0_158
	v_readlane_b32 s100, v254, 47
	v_lshl_add_u32 v251, s54, 8, v139
	v_lshl_or_b32 v144, s53, 8, v153
	s_cmp_lg_u32 s100, 0
	s_cselect_b32 s100, 1, 0
	s_cmp_lt_i32 s53, 16
	s_cselect_b32 s101, 1, 0
	s_and_b32 s100, s100, s101
	s_cmp_lg_u32 s100, 0
	s_cbranch_scc1 .Lpk_setup_gm
	v_lshlrev_b32_e32 v250, 14, v251
	v_lshl_add_u32 v250, v144, 1, v250
	s_mov_b64 s[100:101], s[16:17]
	s_branch .Lpk_setup_done
; #define PG8_STAGE(bufoff, gbase, voff) do { _Pragma("unroll") for (int _i = 0; _i < 2; ++_i) \
;         __builtin_amdgcn_global_load_lds((const unsigned*)((const char*)(gbase) + (voff)[_i]), (LAS unsigned*)(lds + (bufoff) + ldsw + _i * 8192), 16, 0, 0); } while (0)
; #define PG8_LDA(dst, b, h) do { _Pragma("unroll") for (int m = 0; m < 4; ++m) _Pragma("unroll") for (int k = 0; k < 2; ++k) dst[m][k] = *(const LAS bf16x8*)(lds + PG8_SA(b, h) + aoff + m * 2048 + k * 1024); } while (0)
; #define PG8_LDB(dst, b, h) do { _Pragma("unroll") for (int n = 0; n < 2; ++n) _Pragma("unroll") for (int k = 0; k < 2; ++k) dst[n][k] = *(const LAS bf16x8*)(lds + PG8_SB(b, h) + boff + n * 2048 + k * 1024); } while (0)
; #define PG8_WAIT_V(n) asm volatile("s_waitcnt vmcnt(" #n ")" ::: "memory")
; #define PG8_WAIT_L(n) asm volatile("s_waitcnt lgkmcnt(" #n ")" ::: "memory")
; #define PG8_BAR __builtin_amdgcn_s_barrier()
; #define PG8_SCHED __builtin_amdgcn_sched_barrier(0)
; template <class Epi>
; __device__ __forceinline__ void gemm_phase(LAS unsigned char* lds, const Gemm g, const StaticOrder& S, const Epi& E) {
;     ...
;             const bool last = (t == nt - 2);
;             const char* a1 = cA + (size_t)(t + 1) * kstepA;
;             const char* a2 = last ? nA : cA + (size_t)(t + 2) * kstepA; const char* b2 = last ? nB : cB + (size_t)(t + 2) * kstep;
;             const char* a3 = a2 + kstepA; const char* b3 = b2 + kstep;
;             PG8_LDB(B0, 0, 0); PG8_SCHED; PG8_LDA(At, 0, 0); PG8_STAGE(PG8_SA(1, 1), a1 + hstepA, voffA);
;             PG8_WAIT_L(8); PG8_BAR; PG8_WAIT_L(0); PG8_MMA(0, 0, At, B0); PG8_BAR; PG8_SCHED;
;             PG8_LDB(B1, 0, 1); PG8_STAGE(PG8_SB(0, 0), b2, voffB);
;             PG8_BAR; PG8_WAIT_L(0); PG8_MMA(0, 1, At, B1); PG8_BAR;
;             PG8_LDA(At, 0, 1); PG8_STAGE(PG8_SA(0, 0), a2, voffA);
;             PG8_BAR; PG8_WAIT_L(0); PG8_MMA(1, 0, At, B0); PG8_BAR; PG8_SCHED;
;             PG8_STAGE(PG8_SB(0, 1), b2 + hstepB, voffB);
;             PG8_WAIT_V(6); PG8_BAR; PG8_MMA(1, 1, At, B1); PG8_BAR;
;     __device__ __forceinline__ void operator()(const f32x4 (&acc)[2][2][4][2], const Unit& u, int wr, int wc, int fr, int fq, const Pre& pp) const {
;     ...
;                     bf16_t* dst = gm ? UG + (size_t)(c >> 4) * GSTR + r * 16 + (c & 15) : O + (size_t)r * DE2 + c;
.Lpk_setup_gm:
	v_lshrrev_b32_e32 v250, 4, v144
	v_mul_u32_u24_e32 v250, 0x41100, v250
	v_lshl_add_u32 v250, v251, 5, v250
	v_lshl_add_u32 v250, v138, 1, v250
	s_mov_b64 s[100:101], s[18:19]
.Lpk_setup_done:
	s_add_u32 s42, s38, 0x100
	s_addc_u32 s43, s39, 0
	s_add_i32 s60, 0, 0x10000
	v_add_u32_e32 v0, s60, v152
	ds_read_b128 v[146:149], v0
	ds_read_b128 v[162:165], v0 offset:1024
	ds_read_b128 v[166:169], v0 offset:2048
	ds_read_b128 v[170:173], v0 offset:3072
	s_cmp_eq_u32 s59, 28
	s_cselect_b32 s25, s23, s43
	s_cselect_b32 s24, s55, s42
	s_cselect_b32 s5, s21, s58
	s_cselect_b32 s4, s56, s57
	v_lshl_add_u64 v[150:151], s[38:39], 0, v[140:141]
	s_add_i32 m0, s46, 0xc000
	ds_read_b128 v[174:177], v154
	ds_read_b128 v[188:191], v154 offset:1024
	ds_read_b128 v[192:195], v154 offset:2048
	ds_read_b128 v[196:199], v154 offset:3072
	ds_read_b128 v[200:203], v154 offset:4096
	ds_read_b128 v[204:207], v154 offset:5120
	ds_read_b128 v[208:211], v154 offset:6144
	ds_read_b128 v[212:215], v154 offset:7168
	global_load_lds_dwordx4 v[150:151], off
	v_lshl_add_u64 v[150:151], s[38:39], 0, v[142:143]
	s_add_i32 m0, s46, 0xe000
	s_nop 0
	global_load_lds_dwordx4 v[150:151], off
	s_waitcnt lgkmcnt(8)
	s_barrier
	s_waitcnt lgkmcnt(0)
	s_setprio 1
	s_waitcnt lgkmcnt(0)
	v_mfma_f32_16x16x32_bf16 v[126:129], v[146:149], v[174:177], v[126:129]
	v_mfma_f32_16x16x32_bf16 v[122:125], v[166:169], v[174:177], v[122:125]
	v_mfma_f32_16x16x32_bf16 v[110:113], v[146:149], v[192:195], v[110:113]
	v_mfma_f32_16x16x32_bf16 v[106:109], v[166:169], v[192:195], v[106:109]
	v_mfma_f32_16x16x32_bf16 v[94:97], v[146:149], v[200:203], v[94:97]
	v_mfma_f32_16x16x32_bf16 v[90:93], v[166:169], v[200:203], v[90:93]
	v_mfma_f32_16x16x32_bf16 v[78:81], v[146:149], v[208:211], v[78:81]
	v_mfma_f32_16x16x32_bf16 v[74:77], v[166:169], v[208:211], v[74:77]
	v_mfma_f32_16x16x32_bf16 v[126:129], v[162:165], v[188:191], v[126:129]
	v_mfma_f32_16x16x32_bf16 v[122:125], v[170:173], v[188:191], v[122:125]
	v_mfma_f32_16x16x32_bf16 v[110:113], v[162:165], v[196:199], v[110:113]
	v_mfma_f32_16x16x32_bf16 v[106:109], v[170:173], v[196:199], v[106:109]
	v_mfma_f32_16x16x32_bf16 v[94:97], v[162:165], v[204:207], v[94:97]
	v_mfma_f32_16x16x32_bf16 v[90:93], v[170:173], v[204:207], v[90:93]
	v_mfma_f32_16x16x32_bf16 v[78:81], v[162:165], v[212:215], v[78:81]
	v_mfma_f32_16x16x32_bf16 v[74:77], v[170:173], v[212:215], v[74:77]
	s_setprio 0
	s_barrier
	s_add_i32 s61, 0, 0x14000
	s_add_i32 s38, s60, s45
	v_add_u32_e32 v0, s61, v152
	v_lshl_add_u64 v[150:151], s[4:5], 0, v[134:135]
	s_mov_b32 m0, s38
	ds_read_b128 v[216:219], v0
	ds_read_b128 v[220:223], v0 offset:1024
	ds_read_b128 v[224:227], v0 offset:2048
	ds_read_b128 v[228:231], v0 offset:3072
	global_load_lds_dwordx4 v[150:151], off
	v_lshl_add_u64 v[184:185], s[4:5], 0, v[130:131]
	s_add_i32 m0, s38, 0x2000
	s_nop 0
	global_load_lds_dwordx4 v[184:185], off
	s_barrier
	s_waitcnt lgkmcnt(0)
	s_setprio 1
	s_waitcnt lgkmcnt(0)
	v_mfma_f32_16x16x32_bf16 v[118:121], v[216:219], v[174:177], v[118:121]
	v_mfma_f32_16x16x32_bf16 v[114:117], v[224:227], v[174:177], v[114:117]
	v_mfma_f32_16x16x32_bf16 v[102:105], v[216:219], v[192:195], v[102:105]
	v_mfma_f32_16x16x32_bf16 v[98:101], v[224:227], v[192:195], v[98:101]
	v_mfma_f32_16x16x32_bf16 v[86:89], v[216:219], v[200:203], v[86:89]
	v_mfma_f32_16x16x32_bf16 v[82:85], v[224:227], v[200:203], v[82:85]
	v_mfma_f32_16x16x32_bf16 v[70:73], v[216:219], v[208:211], v[70:73]
	v_mfma_f32_16x16x32_bf16 v[66:69], v[224:227], v[208:211], v[66:69]
	v_mfma_f32_16x16x32_bf16 v[118:121], v[220:223], v[188:191], v[118:121]
	v_mfma_f32_16x16x32_bf16 v[114:117], v[228:231], v[188:191], v[114:117]
	v_mfma_f32_16x16x32_bf16 v[102:105], v[220:223], v[196:199], v[102:105]
	v_mfma_f32_16x16x32_bf16 v[98:101], v[228:231], v[196:199], v[98:101]
	v_mfma_f32_16x16x32_bf16 v[86:89], v[220:223], v[204:207], v[86:89]
	v_mfma_f32_16x16x32_bf16 v[82:85], v[228:231], v[204:207], v[82:85]
	v_mfma_f32_16x16x32_bf16 v[70:73], v[220:223], v[212:215], v[70:73]
	v_mfma_f32_16x16x32_bf16 v[66:69], v[228:231], v[212:215], v[66:69]
	s_setprio 0
	s_mov_b32 m0, s46
	v_lshl_add_u64 v[186:187], s[24:25], 0, v[136:137]
	s_barrier
	ds_read_b128 v[174:177], v154 offset:16384
	ds_read_b128 v[188:191], v154 offset:17408
	ds_read_b128 v[192:195], v154 offset:18432
	ds_read_b128 v[196:199], v154 offset:19456
	ds_read_b128 v[200:203], v154 offset:20480
	ds_read_b128 v[204:207], v154 offset:21504
	ds_read_b128 v[208:211], v154 offset:22528
	ds_read_b128 v[212:215], v154 offset:23552
	global_load_lds_dwordx4 v[186:187], off
	v_lshl_add_u64 v[244:245], s[24:25], 0, v[132:133]
	s_mov_b32 m0, s47
	s_nop 0
	global_load_lds_dwordx4 v[244:245], off
	s_barrier
	s_waitcnt lgkmcnt(0)
	s_setprio 1
	s_waitcnt lgkmcnt(0)
	v_mfma_f32_16x16x32_bf16 v[62:65], v[146:149], v[174:177], v[62:65]
	v_mfma_f32_16x16x32_bf16 v[58:61], v[166:169], v[174:177], v[58:61]
	v_mfma_f32_16x16x32_bf16 v[46:49], v[146:149], v[192:195], v[46:49]
	v_mfma_f32_16x16x32_bf16 v[42:45], v[166:169], v[192:195], v[42:45]
	v_mfma_f32_16x16x32_bf16 v[30:33], v[146:149], v[200:203], v[30:33]
	v_mfma_f32_16x16x32_bf16 v[26:29], v[166:169], v[200:203], v[26:29]
	v_mfma_f32_16x16x32_bf16 v[14:17], v[146:149], v[208:211], v[14:17]
	v_mfma_f32_16x16x32_bf16 v[10:13], v[166:169], v[208:211], v[10:13]
	v_mfma_f32_16x16x32_bf16 v[62:65], v[162:165], v[188:191], v[62:65]
	v_mfma_f32_16x16x32_bf16 v[58:61], v[170:173], v[188:191], v[58:61]
	v_mfma_f32_16x16x32_bf16 v[46:49], v[162:165], v[196:199], v[46:49]
	v_mfma_f32_16x16x32_bf16 v[42:45], v[170:173], v[196:199], v[42:45]
	v_mfma_f32_16x16x32_bf16 v[30:33], v[162:165], v[204:207], v[30:33]
	v_mfma_f32_16x16x32_bf16 v[26:29], v[170:173], v[204:207], v[26:29]
	v_mfma_f32_16x16x32_bf16 v[14:17], v[162:165], v[212:215], v[14:17]
	v_mfma_f32_16x16x32_bf16 v[10:13], v[170:173], v[212:215], v[10:13]
	s_setprio 0
	s_barrier
; __device__ __forceinline__ unsigned cvt_pk_bf16(float lo, float hi) { unsigned r; asm volatile("v_cvt_pk_bf16_f32 %0, %1, %2" : "=v"(r) : "v"(lo), "v"(hi)); return r; }
; #define PG8_STAGE(bufoff, gbase, voff) do { _Pragma("unroll") for (int _i = 0; _i < 2; ++_i) \
;         __builtin_amdgcn_global_load_lds((const unsigned*)((const char*)(gbase) + (voff)[_i]), (LAS unsigned*)(lds + (bufoff) + ldsw + _i * 8192), 16, 0, 0); } while (0)
; #define PG8_LDA(dst, b, h) do { _Pragma("unroll") for (int m = 0; m < 4; ++m) _Pragma("unroll") for (int k = 0; k < 2; ++k) dst[m][k] = *(const LAS bf16x8*)(lds + PG8_SA(b, h) + aoff + m * 2048 + k * 1024); } while (0)
; #define PG8_LDB(dst, b, h) do { _Pragma("unroll") for (int n = 0; n < 2; ++n) _Pragma("unroll") for (int k = 0; k < 2; ++k) dst[n][k] = *(const LAS bf16x8*)(lds + PG8_SB(b, h) + boff + n * 2048 + k * 1024); } while (0)
; #define PG8_WAIT_V(n) asm volatile("s_waitcnt vmcnt(" #n ")" ::: "memory")
; #define PG8_WAIT_L(n) asm volatile("s_waitcnt lgkmcnt(" #n ")" ::: "memory")
; template <class Epi>
; __device__ __forceinline__ void gemm_phase(LAS unsigned char* lds, const Gemm g, const StaticOrder& S, const Epi& E) {
;     ...
;             PG8_WAIT_V(6); PG8_BAR; PG8_MMA(1, 1, At, B1); PG8_BAR;
;             PG8_LDB(B0, 1, 0); PG8_SCHED; PG8_LDA(At, 1, 0); PG8_STAGE(PG8_SA(0, 1), a2 + hstepA, voffA);
;             PG8_WAIT_L(8); PG8_BAR; PG8_WAIT_L(0); PG8_MMA(0, 0, At, B0); PG8_BAR; PG8_SCHED;
;             PG8_LDB(B1, 1, 1); PG8_STAGE(PG8_SB(1, 0), b3, voffB);
;             PG8_BAR; PG8_WAIT_L(0); PG8_MMA(0, 1, At, B1); PG8_BAR;
;             PG8_LDA(At, 1, 1); PG8_STAGE(PG8_SA(1, 0), a3, voffA);
;             PG8_BAR; PG8_WAIT_L(0); PG8_MMA(1, 0, At, B0); PG8_BAR; PG8_SCHED;
;     __device__ __forceinline__ void operator()(const f32x4 (&acc)[2][2][4][2], const Unit& u, int wr, int wc, int fr, int fq, const Pre& pp) const {
;     ...
;             for (int m = 0; m < 4; ++m) { const int r = row0 + ai * HALF + m * 16; const float inv = rsqrtf(rs[ai * 4 + m] * (1.0f / DM) + EPS);
; #pragma unroll
;                 for (int bj = 0; bj < 2; ++bj) { const f32x4 v0 = acc[ai][bj][m][0] * inv, v1 = acc[ai][bj][m][1] * inv; const int c = col0 + bj * HALF;
;                     u32x4 w; w.x = cvt_pk_bf16(v0[0], v0[1]); w.y = cvt_pk_bf16(v0[2], v0[3]); w.z = cvt_pk_bf16(v1[0], v1[1]); w.w = cvt_pk_bf16(v1[2], v1[3]);
	s_add_u32 s38, s4, 0x80000
	s_addc_u32 s39, s5, 0
	s_add_i32 s60, s61, s45
	v_lshl_add_u64 v[146:147], s[38:39], 0, v[134:135]
	s_mov_b32 m0, s60
	s_nop 0
	global_load_lds_dwordx4 v[146:147], off
	v_lshl_add_u64 v[146:147], s[38:39], 0, v[130:131]
	s_add_i32 m0, s60, 0x2000
	s_nop 0
	global_load_lds_dwordx4 v[146:147], off
	s_waitcnt vmcnt(6)
	s_barrier
	s_setprio 1
	v_mfma_f32_16x16x32_bf16 v[54:57], v[216:219], v[174:177], v[54:57]
	v_mfma_f32_16x16x32_bf16 v[50:53], v[224:227], v[174:177], v[50:53]
	v_mfma_f32_16x16x32_bf16 v[38:41], v[216:219], v[192:195], v[38:41]
	v_mfma_f32_16x16x32_bf16 v[34:37], v[224:227], v[192:195], v[34:37]
	v_mfma_f32_16x16x32_bf16 v[22:25], v[216:219], v[200:203], v[22:25]
	v_mfma_f32_16x16x32_bf16 v[18:21], v[224:227], v[200:203], v[18:21]
	v_mfma_f32_16x16x32_bf16 v[6:9], v[216:219], v[208:211], v[6:9]
	v_mfma_f32_16x16x32_bf16 v[2:5], v[224:227], v[208:211], v[2:5]
	v_mfma_f32_16x16x32_bf16 v[54:57], v[220:223], v[188:191], v[54:57]
	v_mfma_f32_16x16x32_bf16 v[50:53], v[228:231], v[188:191], v[50:53]
	v_mfma_f32_16x16x32_bf16 v[38:41], v[220:223], v[196:199], v[38:41]
	v_mfma_f32_16x16x32_bf16 v[34:37], v[228:231], v[196:199], v[34:37]
	v_mfma_f32_16x16x32_bf16 v[22:25], v[220:223], v[204:207], v[22:25]
	v_mfma_f32_16x16x32_bf16 v[18:21], v[228:231], v[204:207], v[18:21]
	v_mfma_f32_16x16x32_bf16 v[6:9], v[220:223], v[212:215], v[6:9]
	v_mfma_f32_16x16x32_bf16 v[2:5], v[228:231], v[212:215], v[2:5]
	s_setprio 0
	s_add_i32 s38, 0, 0x18000
	v_add_u32_e32 v0, s38, v152
	s_barrier
	ds_read_b128 v[146:149], v0
	ds_read_b128 v[162:165], v0 offset:1024
	ds_read_b128 v[166:169], v0 offset:2048
	ds_read_b128 v[170:173], v0 offset:3072
	s_add_u32 s24, s24, 0x80000
	s_addc_u32 s25, s25, 0
	s_mov_b32 m0, s48
	v_lshl_add_u64 v[216:217], s[24:25], 0, v[136:137]
	ds_read_b128 v[174:177], v154 offset:32768
	ds_read_b128 v[188:191], v154 offset:33792
	ds_read_b128 v[192:195], v154 offset:34816
	ds_read_b128 v[196:199], v154 offset:35840
	ds_read_b128 v[200:203], v154 offset:36864
	ds_read_b128 v[204:207], v154 offset:37888
	ds_read_b128 v[208:211], v154 offset:38912
	ds_read_b128 v[212:215], v154 offset:39936
	global_load_lds_dwordx4 v[216:217], off
	v_lshl_add_u64 v[216:217], s[24:25], 0, v[132:133]
	s_mov_b32 m0, s49
	s_nop 0
	global_load_lds_dwordx4 v[216:217], off
	s_waitcnt lgkmcnt(8)
	s_barrier
	s_waitcnt lgkmcnt(0)
	s_setprio 1
	s_waitcnt lgkmcnt(0)
	v_mfma_f32_16x16x32_bf16 v[126:129], v[146:149], v[174:177], v[126:129]
	v_mfma_f32_16x16x32_bf16 v[122:125], v[166:169], v[174:177], v[122:125]
	v_mfma_f32_16x16x32_bf16 v[110:113], v[146:149], v[192:195], v[110:113]
	v_mfma_f32_16x16x32_bf16 v[106:109], v[166:169], v[192:195], v[106:109]
	v_mfma_f32_16x16x32_bf16 v[94:97], v[146:149], v[200:203], v[94:97]
	v_mfma_f32_16x16x32_bf16 v[90:93], v[166:169], v[200:203], v[90:93]
	v_mfma_f32_16x16x32_bf16 v[78:81], v[146:149], v[208:211], v[78:81]
	v_mfma_f32_16x16x32_bf16 v[74:77], v[166:169], v[208:211], v[74:77]
	v_mfma_f32_16x16x32_bf16 v[126:129], v[162:165], v[188:191], v[126:129]
	v_mfma_f32_16x16x32_bf16 v[122:125], v[170:173], v[188:191], v[122:125]
	v_mfma_f32_16x16x32_bf16 v[110:113], v[162:165], v[196:199], v[110:113]
	v_mfma_f32_16x16x32_bf16 v[106:109], v[170:173], v[196:199], v[106:109]
	v_mfma_f32_16x16x32_bf16 v[94:97], v[162:165], v[204:207], v[94:97]
	v_mfma_f32_16x16x32_bf16 v[90:93], v[170:173], v[204:207], v[90:93]
	v_mfma_f32_16x16x32_bf16 v[78:81], v[162:165], v[212:215], v[78:81]
	v_mfma_f32_16x16x32_bf16 v[74:77], v[170:173], v[212:215], v[74:77]
	s_setprio 0
	s_barrier
	s_add_i32 s24, 0, 0x1c000
	s_add_i32 s25, s38, s45
	v_add_u32_e32 v0, s24, v152
	v_lshl_add_u64 v[150:151], v[150:151], 0, s[6:7]
	s_mov_b32 m0, s25
	ds_read_b128 v[216:219], v0
	ds_read_b128 v[220:223], v0 offset:1024
	ds_read_b128 v[224:227], v0 offset:2048
	ds_read_b128 v[228:231], v0 offset:3072
	global_load_lds_dwordx4 v[150:151], off
	v_lshl_add_u64 v[150:151], v[184:185], 0, s[6:7]
	s_add_i32 m0, s25, 0x2000
	s_nop 0
	global_load_lds_dwordx4 v[150:151], off
	v_fmamk_f32 v248, v145, 0x3a000000, v233
	v_cmp_gt_f32_e32 vcc, s66, v248
	v_mul_f32_e32 v249, 0x4b800000, v248
	s_nop 0
	v_cndmask_b32_e32 v248, v248, v249, vcc
	v_rsq_f32_e32 v248, v248
	s_nop 0
	v_mul_f32_e32 v249, 0x45800000, v248
	v_cndmask_b32_e32 v145, v248, v249, vcc
	v_fmamk_f32 v248, v161, 0x3a000000, v233
	v_cmp_gt_f32_e32 vcc, s66, v248
	v_mul_f32_e32 v249, 0x4b800000, v248
	s_nop 0
	v_cndmask_b32_e32 v248, v248, v249, vcc
	v_rsq_f32_e32 v248, v248
	s_nop 0
	v_mul_f32_e32 v249, 0x45800000, v248
	v_cndmask_b32_e32 v161, v248, v249, vcc
	v_fmamk_f32 v248, v160, 0x3a000000, v233
	v_cmp_gt_f32_e32 vcc, s66, v248
	v_mul_f32_e32 v249, 0x4b800000, v248
	s_nop 0
	v_cndmask_b32_e32 v248, v248, v249, vcc
	v_rsq_f32_e32 v248, v248
	s_nop 0
	v_mul_f32_e32 v249, 0x45800000, v248
	v_cndmask_b32_e32 v160, v248, v249, vcc
	v_fmamk_f32 v248, v159, 0x3a000000, v233
	v_cmp_gt_f32_e32 vcc, s66, v248
	v_mul_f32_e32 v249, 0x4b800000, v248
	s_nop 0
	v_cndmask_b32_e32 v248, v248, v249, vcc
	v_rsq_f32_e32 v248, v248
	s_nop 0
	v_mul_f32_e32 v249, 0x45800000, v248
	v_cndmask_b32_e32 v159, v248, v249, vcc
	v_mov_b32_e32 v246, v145
	v_pk_mul_f32 v[126:127], v[246:247], v[126:127] op_sel_hi:[0,1]
	v_pk_mul_f32 v[128:129], v[246:247], v[128:129] op_sel_hi:[0,1]
	v_pk_mul_f32 v[122:123], v[246:247], v[122:123] op_sel_hi:[0,1]
	v_pk_mul_f32 v[124:125], v[246:247], v[124:125] op_sel_hi:[0,1]
	v_cvt_pk_bf16_f32 v125, v124, v125
	v_cvt_pk_bf16_f32 v124, v122, v123
	v_cvt_pk_bf16_f32 v122, v126, v127
	v_cvt_pk_bf16_f32 v123, v128, v129
	v_mov_b32_e32 v246, v161
	v_pk_mul_f32 v[110:111], v[246:247], v[110:111] op_sel_hi:[0,1]
	v_pk_mul_f32 v[112:113], v[246:247], v[112:113] op_sel_hi:[0,1]
	v_pk_mul_f32 v[106:107], v[246:247], v[106:107] op_sel_hi:[0,1]
	v_pk_mul_f32 v[108:109], v[246:247], v[108:109] op_sel_hi:[0,1]
	v_cvt_pk_bf16_f32 v109, v108, v109
	v_cvt_pk_bf16_f32 v108, v106, v107
	v_cvt_pk_bf16_f32 v106, v110, v111
	v_cvt_pk_bf16_f32 v107, v112, v113
	v_mov_b32_e32 v246, v160
	v_pk_mul_f32 v[94:95], v[246:247], v[94:95] op_sel_hi:[0,1]
	v_pk_mul_f32 v[96:97], v[246:247], v[96:97] op_sel_hi:[0,1]
	v_pk_mul_f32 v[90:91], v[246:247], v[90:91] op_sel_hi:[0,1]
	v_pk_mul_f32 v[92:93], v[246:247], v[92:93] op_sel_hi:[0,1]
	v_cvt_pk_bf16_f32 v93, v92, v93
	v_cvt_pk_bf16_f32 v92, v90, v91
	v_cvt_pk_bf16_f32 v90, v94, v95
	v_cvt_pk_bf16_f32 v91, v96, v97
	v_mov_b32_e32 v246, v159
	v_pk_mul_f32 v[78:79], v[246:247], v[78:79] op_sel_hi:[0,1]
	v_pk_mul_f32 v[80:81], v[246:247], v[80:81] op_sel_hi:[0,1]
	v_pk_mul_f32 v[74:75], v[246:247], v[74:75] op_sel_hi:[0,1]
	v_pk_mul_f32 v[76:77], v[246:247], v[76:77] op_sel_hi:[0,1]
	v_cvt_pk_bf16_f32 v77, v76, v77
	v_cvt_pk_bf16_f32 v76, v74, v75
	v_cvt_pk_bf16_f32 v74, v78, v79
	v_cvt_pk_bf16_f32 v75, v80, v81
	s_cmp_eq_u32 s100, s16
	s_cbranch_scc0 .Lpk_q00_gm
; __device__ __forceinline__ unsigned cvt_pk_bf16(float lo, float hi) { unsigned r; asm volatile("v_cvt_pk_bf16_f32 %0, %1, %2" : "=v"(r) : "v"(lo), "v"(hi)); return r; }
; #define PG8_STAGE(bufoff, gbase, voff) do { _Pragma("unroll") for (int _i = 0; _i < 2; ++_i) \
;         __builtin_amdgcn_global_load_lds((const unsigned*)((const char*)(gbase) + (voff)[_i]), (LAS unsigned*)(lds + (bufoff) + ldsw + _i * 8192), 16, 0, 0); } while (0)
; #define PG8_LDA(dst, b, h) do { _Pragma("unroll") for (int m = 0; m < 4; ++m) _Pragma("unroll") for (int k = 0; k < 2; ++k) dst[m][k] = *(const LAS bf16x8*)(lds + PG8_SA(b, h) + aoff + m * 2048 + k * 1024); } while (0)
; #define PG8_MMA(ai, bj, At, Bt) do { __builtin_amdgcn_s_setprio(1); _Pragma("unroll") for (int m = 0; m < 4; ++m) _Pragma("unroll") for (int n = 0; n < 2; ++n) _Pragma("unroll") for (int k = 0; k < 2; ++k) \
;         acc[ai][bj][m][n] = __builtin_amdgcn_mfma_f32_16x16x32_bf16(Bt[n][k], At[m][k], acc[ai][bj][m][n], 0, 0, 0); __builtin_amdgcn_s_setprio(0); } while (0)
; #define PG8_WAIT_L(n) asm volatile("s_waitcnt lgkmcnt(" #n ")" ::: "memory")
; #define PG8_BAR __builtin_amdgcn_s_barrier()
; template <class Epi>
; __device__ __forceinline__ void gemm_phase(LAS unsigned char* lds, const Gemm g, const StaticOrder& S, const Epi& E) {
;     ...
;             PG8_BAR; PG8_WAIT_L(0); PG8_MMA(0, 1, At, B1); PG8_BAR;
;             PG8_LDA(At, 1, 1); PG8_STAGE(PG8_SA(1, 0), a3, voffA);
;             PG8_BAR; PG8_WAIT_L(0); PG8_MMA(1, 0, At, B0); PG8_BAR; PG8_SCHED;
;             PG8_STAGE(PG8_SB(1, 1), b3 + hstepB, voffB);
;     __device__ __forceinline__ void operator()(const f32x4 (&acc)[2][2][4][2], const Unit& u, int wr, int wc, int fr, int fq, const Pre& pp) const {
;     ...
;             for (int m = 0; m < 4; ++m) { const int r = row0 + ai * HALF + m * 16; const float inv = rsqrtf(rs[ai * 4 + m] * (1.0f / DM) + EPS);
; #pragma unroll
;                 for (int bj = 0; bj < 2; ++bj) { const f32x4 v0 = acc[ai][bj][m][0] * inv, v1 = acc[ai][bj][m][1] * inv; const int c = col0 + bj * HALF;
;                     u32x4 w; w.x = cvt_pk_bf16(v0[0], v0[1]); w.y = cvt_pk_bf16(v0[2], v0[3]); w.z = cvt_pk_bf16(v1[0], v1[1]); w.w = cvt_pk_bf16(v1[2], v1[3]);
;                     bf16_t* dst = gm ? UG + (size_t)(c >> 4) * GSTR + r * 16 + (c & 15) : O + (size_t)r * DE2 + c;
;                     *(u32x4*)dst = w; } }
	global_store_dwordx4 v250, v[122:125], s[100:101]
	v_add_u32_e32 v251, 0x40000, v250
	global_store_dwordx4 v251, v[106:109], s[100:101]
	v_add_u32_e32 v251, 0x80000, v250
	global_store_dwordx4 v251, v[90:93], s[100:101]
	v_add_u32_e32 v251, 0xc0000, v250
	global_store_dwordx4 v251, v[74:77], s[100:101]
	s_branch .Lpk_q00_end
.Lpk_q00_gm:
	global_store_dwordx4 v250, v[122:125], s[100:101]
	global_store_dwordx4 v250, v[106:109], s[100:101] offset:512
	global_store_dwordx4 v250, v[90:93], s[100:101] offset:1024
	global_store_dwordx4 v250, v[74:77], s[100:101] offset:1536
.Lpk_q00_end:
	s_barrier
	s_waitcnt lgkmcnt(0)
	s_setprio 1
	s_waitcnt lgkmcnt(0)
	v_mfma_f32_16x16x32_bf16 v[118:121], v[216:219], v[174:177], v[118:121]
	v_mfma_f32_16x16x32_bf16 v[114:117], v[224:227], v[174:177], v[114:117]
	v_mfma_f32_16x16x32_bf16 v[102:105], v[216:219], v[192:195], v[102:105]
	v_mfma_f32_16x16x32_bf16 v[98:101], v[224:227], v[192:195], v[98:101]
	v_mfma_f32_16x16x32_bf16 v[86:89], v[216:219], v[200:203], v[86:89]
	v_mfma_f32_16x16x32_bf16 v[82:85], v[224:227], v[200:203], v[82:85]
	v_mfma_f32_16x16x32_bf16 v[70:73], v[216:219], v[208:211], v[70:73]
	v_mfma_f32_16x16x32_bf16 v[66:69], v[224:227], v[208:211], v[66:69]
	v_mfma_f32_16x16x32_bf16 v[118:121], v[220:223], v[188:191], v[118:121]
	v_mfma_f32_16x16x32_bf16 v[114:117], v[228:231], v[188:191], v[114:117]
	v_mfma_f32_16x16x32_bf16 v[102:105], v[220:223], v[196:199], v[102:105]
	v_mfma_f32_16x16x32_bf16 v[98:101], v[228:231], v[196:199], v[98:101]
	v_mfma_f32_16x16x32_bf16 v[86:89], v[220:223], v[204:207], v[86:89]
	v_mfma_f32_16x16x32_bf16 v[82:85], v[228:231], v[204:207], v[82:85]
	v_mfma_f32_16x16x32_bf16 v[70:73], v[220:223], v[212:215], v[70:73]
	v_mfma_f32_16x16x32_bf16 v[66:69], v[228:231], v[212:215], v[66:69]
	s_setprio 0
	s_mov_b32 m0, s50
	v_lshl_add_u64 v[150:151], v[186:187], 0, s[6:7]
	s_barrier
	ds_read_b128 v[174:177], v154 offset:49152
	ds_read_b128 v[188:191], v154 offset:50176
	ds_read_b128 v[192:195], v154 offset:51200
	ds_read_b128 v[196:199], v154 offset:52224
	ds_read_b128 v[200:203], v154 offset:53248
	ds_read_b128 v[204:207], v154 offset:54272
	ds_read_b128 v[208:211], v154 offset:55296
	ds_read_b128 v[212:215], v154 offset:56320
	global_load_lds_dwordx4 v[150:151], off
	v_lshl_add_u64 v[150:151], v[244:245], 0, s[6:7]
	s_mov_b32 m0, s51
	s_nop 0
	global_load_lds_dwordx4 v[150:151], off
	v_mov_b32_e32 v246, v145
	v_pk_mul_f32 v[118:119], v[246:247], v[118:119] op_sel_hi:[0,1]
	v_pk_mul_f32 v[120:121], v[246:247], v[120:121] op_sel_hi:[0,1]
	v_pk_mul_f32 v[114:115], v[246:247], v[114:115] op_sel_hi:[0,1]
	v_pk_mul_f32 v[116:117], v[246:247], v[116:117] op_sel_hi:[0,1]
	v_cvt_pk_bf16_f32 v117, v116, v117
	v_cvt_pk_bf16_f32 v116, v114, v115
	v_cvt_pk_bf16_f32 v114, v118, v119
	v_cvt_pk_bf16_f32 v115, v120, v121
	v_mov_b32_e32 v246, v161
	v_pk_mul_f32 v[102:103], v[246:247], v[102:103] op_sel_hi:[0,1]
	v_pk_mul_f32 v[104:105], v[246:247], v[104:105] op_sel_hi:[0,1]
	v_pk_mul_f32 v[98:99], v[246:247], v[98:99] op_sel_hi:[0,1]
	v_pk_mul_f32 v[100:101], v[246:247], v[100:101] op_sel_hi:[0,1]
	v_cvt_pk_bf16_f32 v101, v100, v101
	v_cvt_pk_bf16_f32 v100, v98, v99
	v_cvt_pk_bf16_f32 v98, v102, v103
	v_cvt_pk_bf16_f32 v99, v104, v105
	v_mov_b32_e32 v246, v160
	v_pk_mul_f32 v[86:87], v[246:247], v[86:87] op_sel_hi:[0,1]
	v_pk_mul_f32 v[88:89], v[246:247], v[88:89] op_sel_hi:[0,1]
	v_pk_mul_f32 v[82:83], v[246:247], v[82:83] op_sel_hi:[0,1]
	v_pk_mul_f32 v[84:85], v[246:247], v[84:85] op_sel_hi:[0,1]
	v_cvt_pk_bf16_f32 v85, v84, v85
	v_cvt_pk_bf16_f32 v84, v82, v83
	v_cvt_pk_bf16_f32 v82, v86, v87
	v_cvt_pk_bf16_f32 v83, v88, v89
	v_mov_b32_e32 v246, v159
	v_pk_mul_f32 v[70:71], v[246:247], v[70:71] op_sel_hi:[0,1]
	v_pk_mul_f32 v[72:73], v[246:247], v[72:73] op_sel_hi:[0,1]
	v_pk_mul_f32 v[66:67], v[246:247], v[66:67] op_sel_hi:[0,1]
	v_pk_mul_f32 v[68:69], v[246:247], v[68:69] op_sel_hi:[0,1]
	v_cvt_pk_bf16_f32 v69, v68, v69
	v_cvt_pk_bf16_f32 v68, v66, v67
	v_cvt_pk_bf16_f32 v66, v70, v71
	v_cvt_pk_bf16_f32 v67, v72, v73
	s_cmp_eq_u32 s100, s16
	s_cbranch_scc0 .Lpk_q01_gm
	global_store_dwordx4 v250, v[114:117], s[100:101] offset:256
	v_add_u32_e32 v251, 0x40000, v250
	global_store_dwordx4 v251, v[98:101], s[100:101] offset:256
	v_add_u32_e32 v251, 0x80000, v250
	global_store_dwordx4 v251, v[82:85], s[100:101] offset:256
	v_add_u32_e32 v251, 0xc0000, v250
	global_store_dwordx4 v251, v[66:69], s[100:101] offset:256
	s_branch .Lpk_q01_end
.Lpk_q01_gm:
	v_add_u32_e32 v251, 0x208800, v250
	global_store_dwordx4 v251, v[114:117], s[100:101]
	global_store_dwordx4 v251, v[98:101], s[100:101] offset:512
	global_store_dwordx4 v251, v[82:85], s[100:101] offset:1024
	global_store_dwordx4 v251, v[66:69], s[100:101] offset:1536
; __device__ __forceinline__ unsigned cvt_pk_bf16(float lo, float hi) { unsigned r; asm volatile("v_cvt_pk_bf16_f32 %0, %1, %2" : "=v"(r) : "v"(lo), "v"(hi)); return r; }
; #define PG8_STAGE(bufoff, gbase, voff) do { _Pragma("unroll") for (int _i = 0; _i < 2; ++_i) \
;         __builtin_amdgcn_global_load_lds((const unsigned*)((const char*)(gbase) + (voff)[_i]), (LAS unsigned*)(lds + (bufoff) + ldsw + _i * 8192), 16, 0, 0); } while (0)
; #define PG8_MMA(ai, bj, At, Bt) do { __builtin_amdgcn_s_setprio(1); _Pragma("unroll") for (int m = 0; m < 4; ++m) _Pragma("unroll") for (int n = 0; n < 2; ++n) _Pragma("unroll") for (int k = 0; k < 2; ++k) \
;         acc[ai][bj][m][n] = __builtin_amdgcn_mfma_f32_16x16x32_bf16(Bt[n][k], At[m][k], acc[ai][bj][m][n], 0, 0, 0); __builtin_amdgcn_s_setprio(0); } while (0)
; #define PG8_WAIT_V(n) asm volatile("s_waitcnt vmcnt(" #n ")" ::: "memory")
; #define PG8_WAIT_L(n) asm volatile("s_waitcnt lgkmcnt(" #n ")" ::: "memory")
; #define PG8_BAR __builtin_amdgcn_s_barrier()
; #define PG8_SCHED __builtin_amdgcn_sched_barrier(0)
; template <class Epi>
; __device__ __forceinline__ void gemm_phase(LAS unsigned char* lds, const Gemm g, const StaticOrder& S, const Epi& E) {
;     ...
;             PG8_BAR; PG8_WAIT_L(0); PG8_MMA(1, 0, At, B0); PG8_BAR; PG8_SCHED;
;             PG8_STAGE(PG8_SB(1, 1), b3 + hstepB, voffB);
;             PG8_WAIT_V(6); PG8_BAR; PG8_MMA(1, 1, At, B1); PG8_BAR;
;     __device__ __forceinline__ void operator()(const f32x4 (&acc)[2][2][4][2], const Unit& u, int wr, int wc, int fr, int fq, const Pre& pp) const {
;     ...
;             for (int m = 0; m < 4; ++m) { const int r = row0 + ai * HALF + m * 16; const float inv = rsqrtf(rs[ai * 4 + m] * (1.0f / DM) + EPS);
; #pragma unroll
;                 for (int bj = 0; bj < 2; ++bj) { const f32x4 v0 = acc[ai][bj][m][0] * inv, v1 = acc[ai][bj][m][1] * inv; const int c = col0 + bj * HALF;
;                     u32x4 w; w.x = cvt_pk_bf16(v0[0], v0[1]); w.y = cvt_pk_bf16(v0[2], v0[3]); w.z = cvt_pk_bf16(v1[0], v1[1]); w.w = cvt_pk_bf16(v1[2], v1[3]);
;                     bf16_t* dst = gm ? UG + (size_t)(c >> 4) * GSTR + r * 16 + (c & 15) : O + (size_t)r * DE2 + c;
;                     *(u32x4*)dst = w; } }
.Lpk_q01_end:
	s_barrier
	s_waitcnt lgkmcnt(0)
	s_setprio 1
	s_waitcnt lgkmcnt(0)
	v_mfma_f32_16x16x32_bf16 v[62:65], v[146:149], v[174:177], v[62:65]
	v_mfma_f32_16x16x32_bf16 v[58:61], v[166:169], v[174:177], v[58:61]
	v_mfma_f32_16x16x32_bf16 v[46:49], v[146:149], v[192:195], v[46:49]
	v_mfma_f32_16x16x32_bf16 v[42:45], v[166:169], v[192:195], v[42:45]
	v_mfma_f32_16x16x32_bf16 v[30:33], v[146:149], v[200:203], v[30:33]
	v_mfma_f32_16x16x32_bf16 v[26:29], v[166:169], v[200:203], v[26:29]
	v_mfma_f32_16x16x32_bf16 v[14:17], v[146:149], v[208:211], v[14:17]
	v_mfma_f32_16x16x32_bf16 v[10:13], v[166:169], v[208:211], v[10:13]
	v_mfma_f32_16x16x32_bf16 v[62:65], v[162:165], v[188:191], v[62:65]
	v_mfma_f32_16x16x32_bf16 v[58:61], v[170:173], v[188:191], v[58:61]
	v_mfma_f32_16x16x32_bf16 v[46:49], v[162:165], v[196:199], v[46:49]
	v_mfma_f32_16x16x32_bf16 v[42:45], v[170:173], v[196:199], v[42:45]
	v_mfma_f32_16x16x32_bf16 v[30:33], v[162:165], v[204:207], v[30:33]
	v_mfma_f32_16x16x32_bf16 v[26:29], v[170:173], v[204:207], v[26:29]
	v_mfma_f32_16x16x32_bf16 v[14:17], v[162:165], v[212:215], v[14:17]
	v_mfma_f32_16x16x32_bf16 v[10:13], v[170:173], v[212:215], v[10:13]
	s_setprio 0
	s_barrier
	s_add_u32 s4, s4, 0x80080
	s_addc_u32 s5, s5, 0
	s_add_i32 s24, s24, s45
	v_lshl_add_u64 v[146:147], s[4:5], 0, v[134:135]
	s_mov_b32 m0, s24
	s_nop 0
	global_load_lds_dwordx4 v[146:147], off
	v_lshl_add_u64 v[146:147], s[4:5], 0, v[130:131]
	s_add_i32 m0, s24, 0x2000
	s_nop 0
	global_load_lds_dwordx4 v[146:147], off
	v_fmamk_f32 v248, v158, 0x3a000000, v233
	v_cmp_gt_f32_e32 vcc, s66, v248
	v_mul_f32_e32 v249, 0x4b800000, v248
	s_nop 0
	v_cndmask_b32_e32 v248, v248, v249, vcc
	v_rsq_f32_e32 v248, v248
	s_nop 0
	v_mul_f32_e32 v249, 0x45800000, v248
	v_cndmask_b32_e32 v158, v248, v249, vcc
	v_fmamk_f32 v248, v157, 0x3a000000, v233
	v_cmp_gt_f32_e32 vcc, s66, v248
	v_mul_f32_e32 v249, 0x4b800000, v248
	s_nop 0
	v_cndmask_b32_e32 v248, v248, v249, vcc
	v_rsq_f32_e32 v248, v248
	s_nop 0
	v_mul_f32_e32 v249, 0x45800000, v248
	v_cndmask_b32_e32 v157, v248, v249, vcc
	v_fmamk_f32 v248, v156, 0x3a000000, v233
	v_cmp_gt_f32_e32 vcc, s66, v248
	v_mul_f32_e32 v249, 0x4b800000, v248
	s_nop 0
	v_cndmask_b32_e32 v248, v248, v249, vcc
	v_rsq_f32_e32 v248, v248
	s_nop 0
	v_mul_f32_e32 v249, 0x45800000, v248
	v_cndmask_b32_e32 v156, v248, v249, vcc
	v_fmamk_f32 v248, v155, 0x3a000000, v233
	v_cmp_gt_f32_e32 vcc, s66, v248
	v_mul_f32_e32 v249, 0x4b800000, v248
	s_nop 0
	v_cndmask_b32_e32 v248, v248, v249, vcc
	v_rsq_f32_e32 v248, v248
	s_nop 0
	v_mul_f32_e32 v249, 0x45800000, v248
	v_cndmask_b32_e32 v155, v248, v249, vcc
	v_mov_b32_e32 v246, v158
	v_pk_mul_f32 v[62:63], v[246:247], v[62:63] op_sel_hi:[0,1]
	v_pk_mul_f32 v[64:65], v[246:247], v[64:65] op_sel_hi:[0,1]
	v_pk_mul_f32 v[58:59], v[246:247], v[58:59] op_sel_hi:[0,1]
	v_pk_mul_f32 v[60:61], v[246:247], v[60:61] op_sel_hi:[0,1]
	v_cvt_pk_bf16_f32 v61, v60, v61
	v_cvt_pk_bf16_f32 v60, v58, v59
	v_cvt_pk_bf16_f32 v58, v62, v63
	v_cvt_pk_bf16_f32 v59, v64, v65
	v_mov_b32_e32 v246, v157
	v_pk_mul_f32 v[46:47], v[246:247], v[46:47] op_sel_hi:[0,1]
	v_pk_mul_f32 v[48:49], v[246:247], v[48:49] op_sel_hi:[0,1]
	v_pk_mul_f32 v[42:43], v[246:247], v[42:43] op_sel_hi:[0,1]
	v_pk_mul_f32 v[44:45], v[246:247], v[44:45] op_sel_hi:[0,1]
	v_cvt_pk_bf16_f32 v45, v44, v45
	v_cvt_pk_bf16_f32 v44, v42, v43
	v_cvt_pk_bf16_f32 v42, v46, v47
	v_cvt_pk_bf16_f32 v43, v48, v49
	v_mov_b32_e32 v246, v156
	v_pk_mul_f32 v[30:31], v[246:247], v[30:31] op_sel_hi:[0,1]
	v_pk_mul_f32 v[32:33], v[246:247], v[32:33] op_sel_hi:[0,1]
	v_pk_mul_f32 v[26:27], v[246:247], v[26:27] op_sel_hi:[0,1]
	v_pk_mul_f32 v[28:29], v[246:247], v[28:29] op_sel_hi:[0,1]
	v_cvt_pk_bf16_f32 v29, v28, v29
	v_cvt_pk_bf16_f32 v28, v26, v27
	v_cvt_pk_bf16_f32 v26, v30, v31
	v_cvt_pk_bf16_f32 v27, v32, v33
	v_mov_b32_e32 v246, v155
	v_pk_mul_f32 v[14:15], v[246:247], v[14:15] op_sel_hi:[0,1]
	v_pk_mul_f32 v[16:17], v[246:247], v[16:17] op_sel_hi:[0,1]
	v_pk_mul_f32 v[10:11], v[246:247], v[10:11] op_sel_hi:[0,1]
	v_pk_mul_f32 v[12:13], v[246:247], v[12:13] op_sel_hi:[0,1]
	v_cvt_pk_bf16_f32 v13, v12, v13
	v_cvt_pk_bf16_f32 v12, v10, v11
	v_cvt_pk_bf16_f32 v10, v14, v15
	v_cvt_pk_bf16_f32 v11, v16, v17
	s_cmp_eq_u32 s100, s16
	s_cbranch_scc0 .Lpk_q10_gm
	v_add_u32_e32 v251, 0x200000, v250
	global_store_dwordx4 v251, v[58:61], s[100:101]
	v_add_u32_e32 v251, 0x240000, v250
	global_store_dwordx4 v251, v[42:45], s[100:101]
	v_add_u32_e32 v251, 0x280000, v250
	global_store_dwordx4 v251, v[26:29], s[100:101]
	v_add_u32_e32 v251, 0x2c0000, v250
	global_store_dwordx4 v251, v[10:13], s[100:101]
	s_branch .Lpk_q10_end
; __device__ __forceinline__ unsigned cvt_pk_bf16(float lo, float hi) { unsigned r; asm volatile("v_cvt_pk_bf16_f32 %0, %1, %2" : "=v"(r) : "v"(lo), "v"(hi)); return r; }
; #define PG8_MMA(ai, bj, At, Bt) do { __builtin_amdgcn_s_setprio(1); _Pragma("unroll") for (int m = 0; m < 4; ++m) _Pragma("unroll") for (int n = 0; n < 2; ++n) _Pragma("unroll") for (int k = 0; k < 2; ++k) \
;         acc[ai][bj][m][n] = __builtin_amdgcn_mfma_f32_16x16x32_bf16(Bt[n][k], At[m][k], acc[ai][bj][m][n], 0, 0, 0); __builtin_amdgcn_s_setprio(0); } while (0)
; #define PG8_WAIT_V(n) asm volatile("s_waitcnt vmcnt(" #n ")" ::: "memory")
; #define PG8_BAR __builtin_amdgcn_s_barrier()
; template <class Epi>
; __device__ __forceinline__ void gemm_phase(LAS unsigned char* lds, const Gemm g, const StaticOrder& S, const Epi& E) {
;     ...
;             PG8_WAIT_V(6); PG8_BAR; PG8_MMA(1, 1, At, B1); PG8_BAR;
;         }
;         if constexpr (!Epi::AFTER_DRAIN) E(acc, cur, wr, wc, fr, fq, pre);
;     __device__ __forceinline__ void operator()(const f32x4 (&acc)[2][2][4][2], const Unit& u, int wr, int wc, int fr, int fq, const Pre& pp) const {
;         const int row0 = u.pm * BM + wr * 64 + fr, col0 = u.pn * BM + wc * 32 + 8 * fq;
;         const bool gm = (UG != nullptr) && (u.pn < DE / BM);
;         const float (&rs)[8] = pp.rs;
; #pragma unroll
;         for (int ai = 0; ai < 2; ++ai)
; #pragma unroll
;             for (int m = 0; m < 4; ++m) { const int r = row0 + ai * HALF + m * 16; const float inv = rsqrtf(rs[ai * 4 + m] * (1.0f / DM) + EPS);
; #pragma unroll
;                 for (int bj = 0; bj < 2; ++bj) { const f32x4 v0 = acc[ai][bj][m][0] * inv, v1 = acc[ai][bj][m][1] * inv; const int c = col0 + bj * HALF;
;                     u32x4 w; w.x = cvt_pk_bf16(v0[0], v0[1]); w.y = cvt_pk_bf16(v0[2], v0[3]); w.z = cvt_pk_bf16(v1[0], v1[1]); w.w = cvt_pk_bf16(v1[2], v1[3]);
;                     bf16_t* dst = gm ? UG + (size_t)(c >> 4) * GSTR + r * 16 + (c & 15) : O + (size_t)r * DE2 + c;
;                     *(u32x4*)dst = w; } }
;     }
.Lpk_q10_gm:
	v_add_u32_e32 v251, 0x1000, v250
	global_store_dwordx4 v251, v[58:61], s[100:101]
	global_store_dwordx4 v251, v[42:45], s[100:101] offset:512
	global_store_dwordx4 v251, v[26:29], s[100:101] offset:1024
	global_store_dwordx4 v251, v[10:13], s[100:101] offset:1536
.Lpk_q10_end:
	s_waitcnt vmcnt(18)
	s_barrier
	s_setprio 1
	v_mfma_f32_16x16x32_bf16 v[54:57], v[216:219], v[174:177], v[54:57]
	v_mfma_f32_16x16x32_bf16 v[50:53], v[224:227], v[174:177], v[50:53]
	v_mfma_f32_16x16x32_bf16 v[38:41], v[216:219], v[192:195], v[38:41]
	v_mfma_f32_16x16x32_bf16 v[34:37], v[224:227], v[192:195], v[34:37]
	v_mfma_f32_16x16x32_bf16 v[22:25], v[216:219], v[200:203], v[22:25]
	v_mfma_f32_16x16x32_bf16 v[18:21], v[224:227], v[200:203], v[18:21]
	v_mfma_f32_16x16x32_bf16 v[6:9], v[216:219], v[208:211], v[6:9]
	v_mfma_f32_16x16x32_bf16 v[2:5], v[224:227], v[208:211], v[2:5]
	v_mfma_f32_16x16x32_bf16 v[54:57], v[220:223], v[188:191], v[54:57]
	v_mfma_f32_16x16x32_bf16 v[50:53], v[228:231], v[188:191], v[50:53]
	v_mfma_f32_16x16x32_bf16 v[38:41], v[220:223], v[196:199], v[38:41]
	v_mfma_f32_16x16x32_bf16 v[34:37], v[228:231], v[196:199], v[34:37]
	v_mfma_f32_16x16x32_bf16 v[22:25], v[220:223], v[204:207], v[22:25]
	v_mfma_f32_16x16x32_bf16 v[18:21], v[228:231], v[204:207], v[18:21]
	v_mfma_f32_16x16x32_bf16 v[6:9], v[220:223], v[212:215], v[6:9]
	v_mfma_f32_16x16x32_bf16 v[2:5], v[228:231], v[212:215], v[2:5]
	s_setprio 0
	s_add_i32 s59, s59, 2
	s_add_u32 s57, s57, 0x100
	s_addc_u32 s58, s58, 0
	s_cmp_gt_u32 s59, 29
	s_mov_b64 s[38:39], s[42:43]
	s_barrier
	s_nop 7
	v_mov_b32_e32 v246, v158
	v_pk_mul_f32 v[54:55], v[246:247], v[54:55] op_sel_hi:[0,1]
	v_pk_mul_f32 v[56:57], v[246:247], v[56:57] op_sel_hi:[0,1]
	v_pk_mul_f32 v[50:51], v[246:247], v[50:51] op_sel_hi:[0,1]
	v_pk_mul_f32 v[52:53], v[246:247], v[52:53] op_sel_hi:[0,1]
	v_cvt_pk_bf16_f32 v53, v52, v53
	v_cvt_pk_bf16_f32 v52, v50, v51
	v_cvt_pk_bf16_f32 v50, v54, v55
	v_cvt_pk_bf16_f32 v51, v56, v57
	v_mov_b32_e32 v246, v157
	v_pk_mul_f32 v[38:39], v[246:247], v[38:39] op_sel_hi:[0,1]
	v_pk_mul_f32 v[40:41], v[246:247], v[40:41] op_sel_hi:[0,1]
	v_pk_mul_f32 v[34:35], v[246:247], v[34:35] op_sel_hi:[0,1]
	v_pk_mul_f32 v[36:37], v[246:247], v[36:37] op_sel_hi:[0,1]
	v_cvt_pk_bf16_f32 v37, v36, v37
	v_cvt_pk_bf16_f32 v36, v34, v35
	v_cvt_pk_bf16_f32 v34, v38, v39
	v_cvt_pk_bf16_f32 v35, v40, v41
	v_mov_b32_e32 v246, v156
	v_pk_mul_f32 v[22:23], v[246:247], v[22:23] op_sel_hi:[0,1]
	v_pk_mul_f32 v[24:25], v[246:247], v[24:25] op_sel_hi:[0,1]
	v_pk_mul_f32 v[18:19], v[246:247], v[18:19] op_sel_hi:[0,1]
	v_pk_mul_f32 v[20:21], v[246:247], v[20:21] op_sel_hi:[0,1]
	v_cvt_pk_bf16_f32 v21, v20, v21
	v_cvt_pk_bf16_f32 v20, v18, v19
	v_cvt_pk_bf16_f32 v18, v22, v23
	v_cvt_pk_bf16_f32 v19, v24, v25
	v_mov_b32_e32 v246, v155
	v_pk_mul_f32 v[6:7], v[246:247], v[6:7] op_sel_hi:[0,1]
	v_pk_mul_f32 v[8:9], v[246:247], v[8:9] op_sel_hi:[0,1]
	v_pk_mul_f32 v[2:3], v[246:247], v[2:3] op_sel_hi:[0,1]
	v_pk_mul_f32 v[4:5], v[246:247], v[4:5] op_sel_hi:[0,1]
	v_cvt_pk_bf16_f32 v5, v4, v5
	v_cvt_pk_bf16_f32 v4, v2, v3
	v_cvt_pk_bf16_f32 v2, v6, v7
	v_cvt_pk_bf16_f32 v3, v8, v9
	s_cmp_eq_u32 s100, s16
	s_cbranch_scc0 .Lpk_q11_gm
	v_add_u32_e32 v251, 0x200000, v250
	global_store_dwordx4 v251, v[50:53], s[100:101] offset:256
	v_add_u32_e32 v251, 0x240000, v250
	global_store_dwordx4 v251, v[34:37], s[100:101] offset:256
	v_add_u32_e32 v251, 0x280000, v250
	global_store_dwordx4 v251, v[18:21], s[100:101] offset:256
	v_add_u32_e32 v251, 0x2c0000, v250
	global_store_dwordx4 v251, v[2:5], s[100:101] offset:256
	s_branch .Lpk_q11_end
.Lpk_q11_gm:
	v_add_u32_e32 v251, 0x209800, v250
	global_store_dwordx4 v251, v[50:53], s[100:101]
	global_store_dwordx4 v251, v[34:37], s[100:101] offset:512
	global_store_dwordx4 v251, v[18:21], s[100:101] offset:1024
	global_store_dwordx4 v251, v[2:5], s[100:101] offset:1536
.Lpk_q11_end:
	s_andn2_b64 vcc, exec, s[40:41]
	s_mov_b64 s[4:5], -1
	s_cbranch_vccnz .LBB0_150
	s_nop 0
	v_lshl_add_u32 v2, s22, 8, v139
	v_ashrrev_i32_e32 v3, 31, v2
	v_lshl_add_u64 v[2:3], v[2:3], 2, s[14:15]
	global_load_dword v145, v[2:3], off
	global_load_dword v161, v[2:3], off offset:64
	global_load_dword v160, v[2:3], off offset:128
	global_load_dword v159, v[2:3], off offset:192
	global_load_dword v158, v[2:3], off offset:512
	global_load_dword v157, v[2:3], off offset:576
	global_load_dword v156, v[2:3], off offset:640
	global_load_dword v155, v[2:3], off offset:704
	s_mov_b64 s[4:5], 0
	s_branch .LBB0_150

; __global__ void __launch_bounds__(NTHREADS, 2) fwd_megakernel(Params p_unused) {
	.amdhsa_kernel _Z14fwd_megakernel6Params
		.amdhsa_group_segment_fixed_size 0
		.amdhsa_private_segment_fixed_size 0
		.amdhsa_kernarg_size 432
		.amdhsa_user_sgpr_count 2
		.amdhsa_user_sgpr_dispatch_ptr 0
		.amdhsa_user_sgpr_queue_ptr 0
		.amdhsa_user_sgpr_kernarg_segment_ptr 1
		.amdhsa_user_sgpr_dispatch_id 0
		.amdhsa_user_sgpr_kernarg_preload_length 0
		.amdhsa_user_sgpr_kernarg_preload_offset 0
		.amdhsa_user_sgpr_private_segment_size 0
		.amdhsa_uses_dynamic_stack 0
		.amdhsa_enable_private_segment 0
		.amdhsa_system_sgpr_workgroup_id_x 1
		.amdhsa_system_sgpr_workgroup_id_y 0
		.amdhsa_system_sgpr_workgroup_id_z 0
		.amdhsa_system_sgpr_workgroup_info 0
		.amdhsa_system_vgpr_workitem_id 2
		.amdhsa_next_free_vgpr 255
		.amdhsa_next_free_sgpr 102
		.amdhsa_accum_offset 256
		.amdhsa_reserve_vcc 1
		.amdhsa_float_round_mode_32 0
		.amdhsa_float_round_mode_16_64 0
		.amdhsa_float_denorm_mode_32 3
		.amdhsa_float_denorm_mode_16_64 3
		.amdhsa_dx10_clamp 1
		.amdhsa_ieee_mode 1
		.amdhsa_fp16_overflow 0
		.amdhsa_tg_split 0
		.amdhsa_exception_fp_ieee_invalid_op 0
		.amdhsa_exception_fp_denorm_src 0
		.amdhsa_exception_fp_ieee_div_zero 0
		.amdhsa_exception_fp_ieee_overflow 0
		.amdhsa_exception_fp_ieee_underflow 0
		.amdhsa_exception_fp_ieee_inexact 0
		.amdhsa_exception_int_div_zero 0
	.end_amdhsa_kernel

; __global__ void __launch_bounds__(NTHREADS, 2) fwd_megakernel(Params p_unused) {
amdhsa.kernels:
  - .agpr_count:     0
    .args:
      - .offset:         0
        .size:           176
        .value_kind:     by_value
      - .offset:         176
        .size:           4
        .value_kind:     hidden_block_count_x
      - .offset:         180
        .size:           4
        .value_kind:     hidden_block_count_y
      - .offset:         184
        .size:           4
        .value_kind:     hidden_block_count_z
      - .offset:         188
        .size:           2
        .value_kind:     hidden_group_size_x
      - .offset:         190
        .size:           2
        .value_kind:     hidden_group_size_y
      - .offset:         192
        .size:           2
        .value_kind:     hidden_group_size_z
      - .offset:         194
        .size:           2
        .value_kind:     hidden_remainder_x
      - .offset:         196
        .size:           2
        .value_kind:     hidden_remainder_y
      - .offset:         198
        .size:           2
        .value_kind:     hidden_remainder_z
      - .offset:         216
        .size:           8
        .value_kind:     hidden_global_offset_x
      - .offset:         224
        .size:           8
        .value_kind:     hidden_global_offset_y
      - .offset:         232
        .size:           8
        .value_kind:     hidden_global_offset_z
      - .offset:         240
        .size:           2
        .value_kind:     hidden_grid_dims
      - .offset:         264
        .size:           8
        .value_kind:     hidden_multigrid_sync_arg
      - .offset:         296
        .size:           4
        .value_kind:     hidden_dynamic_lds_size
    .group_segment_fixed_size: 0
    .kernarg_segment_align: 8
    .kernarg_segment_size: 432
    .language:       OpenCL C
    .language_version:
      - 2
      - 0
    .max_flat_workgroup_size: 512
    .name:           _Z14fwd_megakernel6Params
    .private_segment_fixed_size: 0
    .sgpr_count:     108
    .sgpr_spill_count: 140
    .symbol:         _Z14fwd_megakernel6Params.kd
    .uniform_work_group_size: 1
    .uses_dynamic_stack: false
    .vgpr_count:     255
    .vgpr_spill_count: 0
    .wavefront_size: 64
